# NA attention: batched unconditional relative-bias LDS loads + cndmask instead of 16 exec-masked LDS round trips per half; de-serialized group-norm rescale passes; pipelined phase-0 resid
# speedup vs baseline: 1.0175x; 1.0071x over previous
; DI float fexp2(float x) { return __builtin_amdgcn_exp2f(x); }
; DI int crow(int i, int h) { return (i & 3) + 8 * (i >> 2) + 4 * h; }
; template <int NCH, int MODE, bool BOUND> ...
;     ...
;     if (MODE == 2) {
;       const float* sbr = na.sb + (2 * t + hf - na.rq + 7) * 31;
; #pragma unroll
;       for (int i = 0; i < 16; ++i) {
;         const int kc0 = crow(i, h), kc1 = 32 + crow(i, h);
;         const int dc0 = min(max(kc0 - na.cq + 15, 0), 30), dc1 = min(max(kc1 - na.cq + 15, 0), 30);
;         const float b0 = sbr[dc0], b1 = sbr[dc1];
;         s0[i] = ((unsigned)(kc0 - na.c0) < 16u) ? s0[i] + b0 : -1e30f;
;         s1[i] = ((unsigned)(kc1 - na.c0) < 16u) ? s1[i] + b1 : -1e30f;
;       }
;     }
;     ...
;     if (BOUND) {
;       float ps = 0.f;
; #pragma unroll
;       for (int i = 0; i < 16; ++i) {
;         s0[i] = fexp2(s0[i]);
;         s1[i] = fexp2(s1[i]);
;         ps += s0[i] + s1[i];
;       }
;       l += ps;
.LBB0_217:
	s_bitcmp1_b32 s9, 0
	s_cselect_b32 s2, 0xac00, 0
	s_add_i32 s31, s2, 0
	v_cmp_ge_u32_e32 vcc, s8, v136
	v_cmp_lt_u32_e64 s[6:7], s8, v141
	s_and_b64 s[6:7], vcc, s[6:7]
	v_add3_u32 v194, s31, v103, v0
	v_add_u32_e32 v193, v192, v191
	s_and_saveexec_b64 s[2:3], s[6:7]
	s_cbranch_execz .LBB0_251
	ds_read_b128 v[48:51], v194
	ds_read_b128 v[196:199], v194 offset:32
	ds_read_b128 v[52:55], v194 offset:4608
	ds_read_b128 v[200:203], v194 offset:4640
	ds_read_b128 v[204:207], v194 offset:64
	ds_read_b128 v[208:211], v194 offset:96
	ds_read_b128 v[218:221], v194 offset:4672
	ds_read_b128 v[222:225], v194 offset:4704
	s_waitcnt lgkmcnt(7)
	v_mfma_f32_32x32x16_bf16 v[64:79], v[48:51], v[84:87], 0
	v_mov_b32_e32 v195, 0xf149f2ca
	s_waitcnt lgkmcnt(5)
	v_mfma_f32_32x32x16_bf16 v[48:63], v[52:55], v[84:87], 0
	v_mfma_f32_32x32x16_bf16 v[64:79], v[196:199], v[88:91], v[64:79]
	ds_read_b32 v196, v193
	v_mov_b32_e32 v197, 0xf149f2ca
	s_waitcnt lgkmcnt(5)
	v_mfma_f32_32x32x16_bf16 v[48:63], v[200:203], v[88:91], v[48:63]
	s_waitcnt lgkmcnt(4)
	v_mfma_f32_32x32x16_bf16 v[64:79], v[204:207], v[92:95], v[64:79]
	s_waitcnt lgkmcnt(2)
	v_mfma_f32_32x32x16_bf16 v[48:63], v[218:221], v[92:95], v[48:63]
	v_mfma_f32_32x32x16_bf16 v[64:79], v[208:211], v[96:99], v[64:79]
	s_waitcnt lgkmcnt(1)
	v_mfma_f32_32x32x16_bf16 v[48:63], v[222:225], v[96:99], v[48:63]
	v_add_u32_e32 v218, v192, v129
	ds_read_b32 v218, v218
	v_add_u32_e32 v219, v192, v127
	ds_read_b32 v219, v219
	v_add_u32_e32 v220, v192, v125
	ds_read_b32 v220, v220
	v_add_u32_e32 v221, v192, v122
	ds_read_b32 v221, v221
	v_add_u32_e32 v222, v192, v120
	ds_read_b32 v222, v222
	v_add_u32_e32 v223, v192, v118
	ds_read_b32 v223, v223
	v_add_u32_e32 v224, v192, v110
	ds_read_b32 v224, v224
	v_add_u32_e32 v225, v192, v108
	ds_read_b32 v225, v225
	s_waitcnt lgkmcnt(0)
	v_add_f32_e32 v218, v72, v218
	v_add_f32_e32 v219, v73, v219
	v_add_f32_e32 v220, v74, v220
	v_add_f32_e32 v221, v75, v221
	v_add_f32_e32 v222, v76, v222
	v_add_f32_e32 v223, v77, v223
	v_add_f32_e32 v224, v78, v224
	v_add_f32_e32 v225, v79, v225
	v_add_u32_e32 v197, v192, v190
	ds_read_b32 v197, v197
	v_add_u32_e32 v195, v192, v188
	ds_read_b32 v195, v195
	v_add_u32_e32 v198, v192, v186
	ds_read_b32 v198, v198
	v_add_u32_e32 v78, v192, v184
	ds_read_b32 v78, v78
	v_add_u32_e32 v199, v192, v182
	ds_read_b32 v199, v199
	v_add_u32_e32 v79, v192, v135
	ds_read_b32 v79, v79
	v_add_u32_e32 v72, v192, v133
	ds_read_b32 v72, v72
	v_add_u32_e32 v73, v192, v131
	ds_read_b32 v73, v73
	v_add_u32_e32 v200, v192, v189
	ds_read_b32 v200, v200
	v_add_u32_e32 v201, v192, v187
	ds_read_b32 v201, v201
	v_add_u32_e32 v202, v192, v185
	ds_read_b32 v202, v202
	v_add_u32_e32 v203, v192, v183
	ds_read_b32 v203, v203
	v_add_u32_e32 v204, v192, v181
	ds_read_b32 v204, v204
	v_add_u32_e32 v205, v192, v134
	ds_read_b32 v205, v205
	v_add_u32_e32 v206, v192, v132
	ds_read_b32 v206, v206
	v_add_u32_e32 v207, v192, v130
	ds_read_b32 v207, v207
	v_add_u32_e32 v208, v192, v128
	ds_read_b32 v208, v208
	v_add_u32_e32 v209, v192, v126
	ds_read_b32 v209, v209
	v_add_u32_e32 v210, v192, v124
	ds_read_b32 v210, v210
	v_add_u32_e32 v211, v192, v121
	ds_read_b32 v211, v211
	v_add_u32_e32 v76, v192, v119
	ds_read_b32 v76, v76
	v_add_u32_e32 v212, v192, v111
	ds_read_b32 v212, v212
	v_add_u32_e32 v77, v192, v109
	ds_read_b32 v77, v77
	s_waitcnt lgkmcnt(0)
	v_add_f32_e32 v197, v64, v197
	v_add_f32_e32 v195, v65, v195
	v_add_f32_e32 v198, v66, v198
	v_add_f32_e32 v78, v67, v78
	v_add_f32_e32 v199, v68, v199
	v_add_f32_e32 v79, v69, v79
	v_add_f32_e32 v72, v70, v72
	v_add_f32_e32 v73, v71, v73
	v_mov_b32_e32 v166, 0xf149f2ca
	s_mov_b64 vcc, s[38:39]
	s_nop 0
	v_cndmask_b32_e32 v197, v166, v197, vcc
	s_mov_b64 vcc, s[42:43]
	s_nop 0
	v_cndmask_b32_e32 v195, v166, v195, vcc
	s_mov_b64 vcc, s[46:47]
	s_nop 0
	v_cndmask_b32_e32 v198, v166, v198, vcc
	s_mov_b64 vcc, s[54:55]
	s_nop 0
	v_cndmask_b32_e32 v199, v166, v199, vcc
	s_mov_b64 vcc, s[50:51]
	s_nop 0
	v_cndmask_b32_e32 v64, v166, v78, vcc
	s_mov_b64 vcc, s[58:59]
	s_nop 0
	v_cndmask_b32_e32 v67, v166, v79, vcc
	s_mov_b64 vcc, s[62:63]
	s_nop 0
	v_cndmask_b32_e32 v66, v166, v72, vcc
	s_mov_b64 vcc, s[66:67]
	s_nop 0
	v_cndmask_b32_e32 v65, v166, v73, vcc
	s_mov_b64 vcc, s[70:71]
	s_nop 0
	v_cndmask_b32_e32 v69, v166, v218, vcc
	s_mov_b64 vcc, s[74:75]
	s_nop 0
	v_cndmask_b32_e32 v68, v166, v219, vcc
	s_mov_b64 vcc, s[78:79]
	s_nop 0
	v_cndmask_b32_e32 v71, v166, v220, vcc
	s_mov_b64 vcc, s[82:83]
	s_nop 0
	v_cndmask_b32_e32 v70, v166, v221, vcc
	s_mov_b64 vcc, s[86:87]
	s_nop 0
	v_cndmask_b32_e32 v73, v166, v222, vcc
	s_mov_b64 vcc, s[90:91]
	s_nop 0
	v_cndmask_b32_e32 v72, v166, v223, vcc
	s_mov_b64 vcc, s[94:95]
	s_nop 0
	v_cndmask_b32_e32 v75, v166, v224, vcc
	s_mov_b64 vcc, s[0:1]
	s_nop 0
	v_cndmask_b32_e32 v74, v166, v225, vcc
	s_waitcnt lgkmcnt(14)
	v_add_f32_e32 v48, v48, v196
	v_add_f32_e32 v49, v49, v200
	v_cndmask_b32_e64 v48, v240, v48, s[40:41]
	s_waitcnt lgkmcnt(6)
	v_add_f32_e32 v57, v57, v208
	v_add_f32_e32 v51, v51, v202
	v_cndmask_b32_e64 v49, v240, v49, s[44:45]
	v_exp_f32_e32 v196, v197
	v_exp_f32_e32 v197, v48
	v_cndmask_b32_e64 v166, v240, v57, s[76:77]
	v_cndmask_b32_e64 v57, v240, v51, s[52:53]
	v_exp_f32_e32 v51, v195
	v_exp_f32_e32 v49, v49
	s_waitcnt lgkmcnt(1)
	v_add_f32_e32 v62, v62, v212
	v_add_f32_e32 v56, v56, v207
	v_add_f32_e32 v52, v52, v203
	v_add_f32_e32 v50, v50, v201
	v_cndmask_b32_e64 v78, v240, v62, s[96:97]
	v_cndmask_b32_e64 v62, v240, v56, s[72:73]
	v_cndmask_b32_e64 v56, v240, v52, s[56:57]
	v_cndmask_b32_e64 v52, v240, v50, s[48:49]
	s_waitcnt lgkmcnt(0)
; #define MFMA(a, b, c) __builtin_amdgcn_mfma_f32_32x32x16_bf16((a), (b), (c), 0, 0, 0)
; DI float fexp2(float x) { return __builtin_amdgcn_exp2f(x); }
; template <int NCH, int MODE, bool BOUND> ...
;     ...
;     if (BOUND) {
;       float ps = 0.f;
; #pragma unroll
;       for (int i = 0; i < 16; ++i) {
;         s0[i] = fexp2(s0[i]);
;         s1[i] = fexp2(s1[i]);
;         ps += s0[i] + s1[i];
;       }
;       l += ps;
;     ...
;     const char* vb0 = cur + A_VOFF + r * V_ROW + hf * 128 + 16 * h;
; #pragma unroll
;     for (int kb = 0; kb < 2; ++kb)
; #pragma unroll
;       for (int s = 0; s < 2; ++s) {
;         uint4 pu;
;         if (kb == 0) {
;           pu.x = pk_bf16(s0[8 * s + 0], s0[8 * s + 1]); pu.y = pk_bf16(s0[8 * s + 2], s0[8 * s + 3]);
;           pu.z = pk_bf16(s0[8 * s + 4], s0[8 * s + 5]); pu.w = pk_bf16(s0[8 * s + 6], s0[8 * s + 7]);
;         } else {
;           pu.x = pk_bf16(s1[8 * s + 0], s1[8 * s + 1]); pu.y = pk_bf16(s1[8 * s + 2], s1[8 * s + 3]);
;           pu.z = pk_bf16(s1[8 * s + 4], s1[8 * s + 5]); pu.w = pk_bf16(s1[8 * s + 6], s1[8 * s + 7]);
;         }
;         const bf16x8 pf = __builtin_bit_cast(bf16x8, pu);
;         const int koff = (kb * 32 + 16 * s) * 2;
;         {
;           const bf16x8 vf = *(const bf16x8*)(vb0 + koff);
;           o0 = MFMA(vf, pf, o0);
;         }
;         {
;           const bf16x8 vf = *(const bf16x8*)(vb0 + 32 * V_ROW + koff);
;           o1 = MFMA(vf, pf, o1);
;         }
;       }
;   };
; #pragma nounroll
;   for (int t = t0; t < t1; ++t) {
;     const char* cur = smem + ((t - t0) & 1) * A_STAGE;
;     const bool more = (t + 1 < t1);
;     if (more) gload_k(t + 1);
;     f32x16 a0, a1, c0, c1;
;     if (MODE == 2) {
;       if (more) gload_v(t + 1);
;       const bool act0 = (2 * t >= na.r0q) && (2 * t < na.r0q + 8), act1 = (2 * t + 1 >= na.r0q) && (2 * t + 1 < na.r0q + 8);
;       if (act0) { stage_qk(cur, t, 0, a0, a1); stage_pv(cur, 0, a0, a1); }
;       if (act1) { stage_qk(cur, t, 1, c0, c1); stage_pv(cur, 1, c0, c1); }
	v_add_f32_e32 v50, v63, v77
	v_add_f32_e32 v58, v58, v209
	v_add_f32_e32 v55, v55, v206
	v_add_f32_e32 v54, v54, v205
	v_cndmask_b32_e64 v77, v240, v50, s[4:5]
	v_add_f32_e32 v48, v197, v196
	v_mov_b32_e32 v50, v1
	v_add_f32_e32 v59, v59, v210
	v_cndmask_b32_e64 v79, v240, v58, s[80:81]
	v_cndmask_b32_e64 v167, v240, v55, s[68:69]
	v_cndmask_b32_e64 v58, v240, v54, s[64:65]
	v_add_f32_e32 v53, v53, v204
	v_pk_add_f32 v[54:55], v[48:49], v[50:51]
	v_exp_f32_e32 v48, v198
	v_exp_f32_e32 v195, v52
	v_exp_f32_e32 v198, v57
	v_add_f32_e32 v61, v61, v76
	v_cndmask_b32_e64 v76, v240, v59, s[84:85]
	v_cndmask_b32_e64 v59, v240, v53, s[60:61]
	v_exp_f32_e32 v53, v64
	v_pk_add_f32 v[54:55], v[54:55], v[54:55] op_sel:[0,1] op_sel_hi:[1,0]
	v_add_f32_e32 v52, v195, v48
	v_mov_b32_e32 v55, v198
	v_pk_add_f32 v[54:55], v[54:55], v[52:53]
	v_exp_f32_e32 v52, v199
	v_exp_f32_e32 v199, v56
	v_exp_f32_e32 v200, v59
	v_exp_f32_e32 v57, v67
	v_pk_add_f32 v[54:55], v[54:55], v[54:55] op_sel:[0,1] op_sel_hi:[1,0]
	v_add_f32_e32 v56, v199, v52
	v_mov_b32_e32 v55, v200
	v_pk_add_f32 v[54:55], v[54:55], v[56:57]
	v_exp_f32_e32 v56, v66
	v_exp_f32_e32 v201, v58
	v_exp_f32_e32 v167, v167
	v_exp_f32_e32 v59, v65
	v_pk_add_f32 v[54:55], v[54:55], v[54:55] op_sel:[0,1] op_sel_hi:[1,0]
	v_exp_f32_e32 v202, v69
	v_exp_f32_e32 v203, v62
	v_exp_f32_e32 v166, v166
	v_add_f32_e32 v58, v201, v56
	v_mov_b32_e32 v55, v167
	v_exp_f32_e32 v63, v68
	v_pk_add_f32 v[54:55], v[54:55], v[58:59]
	v_add_f32_e32 v62, v203, v202
	v_pk_add_f32 v[54:55], v[54:55], v[54:55] op_sel:[0,1] op_sel_hi:[1,0]
	v_exp_f32_e32 v65, v70
	v_mov_b32_e32 v55, v166
	v_pk_add_f32 v[54:55], v[54:55], v[62:63]
	v_exp_f32_e32 v62, v71
	v_exp_f32_e32 v71, v79
	v_exp_f32_e32 v70, v76
	v_add_f32_e32 v60, v60, v211
	v_pk_add_f32 v[54:55], v[54:55], v[54:55] op_sel:[0,1] op_sel_hi:[1,0]
	v_cndmask_b32_e64 v61, v240, v61, s[92:93]
	v_cndmask_b32_e64 v60, v240, v60, s[88:89]
	v_add_f32_e32 v64, v71, v62
	v_mov_b32_e32 v55, v70
	v_pk_add_f32 v[54:55], v[54:55], v[64:65]
	v_exp_f32_e32 v64, v73
	v_exp_f32_e32 v73, v60
	v_exp_f32_e32 v67, v72
	v_exp_f32_e32 v72, v61
	v_pk_add_f32 v[54:55], v[54:55], v[54:55] op_sel:[0,1] op_sel_hi:[1,0]
	v_add_f32_e32 v66, v73, v64
	v_exp_f32_e32 v69, v74
	v_mov_b32_e32 v55, v72
	v_pk_add_f32 v[54:55], v[54:55], v[66:67]
	v_exp_f32_e32 v66, v75
	v_exp_f32_e32 v75, v78
	v_exp_f32_e32 v74, v77
	v_pk_add_f32 v[54:55], v[54:55], v[54:55] op_sel:[0,1] op_sel_hi:[1,0]
	v_cvt_pk_bf16_f32 v52, v52, v57
	v_add_f32_e32 v68, v75, v66
	v_mov_b32_e32 v55, v74
	v_pk_add_f32 v[54:55], v[54:55], v[68:69]
	v_add3_u32 v68, s31, v107, v0
	v_add_f32_e32 v50, v54, v55
	v_add_f32_e32 v123, v123, v50
	v_cvt_pk_bf16_f32 v50, v196, v51
	v_cvt_pk_bf16_f32 v51, v48, v53
	v_cvt_pk_bf16_f32 v53, v56, v59
	ds_read_b128 v[54:57], v68 offset:26624
	ds_read_b128 v[58:61], v68 offset:26656
	s_waitcnt lgkmcnt(1)
	v_mfma_f32_32x32x16_bf16 v[32:47], v[54:57], v[50:53], v[32:47]
	ds_read_b128 v[54:57], v68 offset:35328
	v_cvt_pk_bf16_f32 v48, v197, v49
	v_cvt_pk_bf16_f32 v49, v195, v198
	s_waitcnt lgkmcnt(0)
	v_mfma_f32_32x32x16_bf16 v[16:31], v[54:57], v[50:53], v[16:31]
	ds_read_b128 v[54:57], v68 offset:35360
	v_cvt_pk_bf16_f32 v50, v202, v63
	v_cvt_pk_bf16_f32 v51, v62, v65
	v_cvt_pk_bf16_f32 v52, v64, v67
	v_cvt_pk_bf16_f32 v53, v66, v69
	s_nop 1
	v_mfma_f32_32x32x16_bf16 v[32:47], v[58:61], v[50:53], v[32:47]
	s_waitcnt lgkmcnt(0)
	v_mfma_f32_32x32x16_bf16 v[16:31], v[54:57], v[50:53], v[16:31]
	ds_read_b128 v[52:55], v68 offset:26688
	v_cvt_pk_bf16_f32 v50, v199, v200
	v_cvt_pk_bf16_f32 v51, v201, v167
	s_waitcnt lgkmcnt(0)
	s_nop 0
	v_mfma_f32_32x32x16_bf16 v[32:47], v[52:55], v[48:51], v[32:47]
	ds_read_b128 v[52:55], v68 offset:35392
	s_waitcnt lgkmcnt(0)
	v_mfma_f32_32x32x16_bf16 v[16:31], v[52:55], v[48:51], v[16:31]
	ds_read_b128 v[52:55], v68 offset:26720
	v_cvt_pk_bf16_f32 v48, v203, v166
	v_cvt_pk_bf16_f32 v49, v71, v70
	v_cvt_pk_bf16_f32 v50, v73, v72
	v_cvt_pk_bf16_f32 v51, v75, v74
	s_waitcnt lgkmcnt(0)
	s_nop 0
	v_mfma_f32_32x32x16_bf16 v[32:47], v[52:55], v[48:51], v[32:47]
	ds_read_b128 v[52:55], v68 offset:35424
	s_waitcnt lgkmcnt(0)
	v_mfma_f32_32x32x16_bf16 v[16:31], v[52:55], v[48:51], v[16:31]
.LBB0_251:
	s_or_b64 exec, exec, s[2:3]
	s_add_i32 s2, s8, 1
	v_cmp_ge_u32_e32 vcc, s2, v136
	v_cmp_lt_u32_e64 s[6:7], s8, v142
	s_and_b64 s[6:7], vcc, s[6:7]
	s_and_saveexec_b64 s[2:3], s[6:7]
	s_cbranch_execz .LBB0_285
; #define MFMA(a, b, c) __builtin_amdgcn_mfma_f32_32x32x16_bf16((a), (b), (c), 0, 0, 0)
; DI int crow(int i, int h) { return (i & 3) + 8 * (i >> 2) + 4 * h; }
; template <int NCH, int MODE, bool BOUND> ...
;     ...
;     const char* kb0 = cur + (hf * 64 + r) * KSTR + h * 16;
;     constexpr int NC2 = NCH < 2 ? NCH : 2;
;     bf16x8 ka[NC2][2], kb[NC2][2], kc[2], kd[2];
; #pragma unroll
;     for (int c = 0; c < NC2; ++c)
; #pragma unroll
;       for (int ks = 0; ks < 2; ++ks) {
;         ka[c][ks] = *(const bf16x8*)(kb0 + c * 64 + ks * 32);
;         kb[c][ks] = *(const bf16x8*)(kb0 + 32 * KSTR + c * 64 + ks * 32);
;       }
;     __builtin_amdgcn_sched_barrier(0);
;     if (NCH == 3) {
; #pragma unroll
;       for (int ks = 0; ks < 2; ++ks) {
;         kc[ks] = *(const bf16x8*)(kb0 + 2 * 64 + ks * 32);
;         kd[ks] = *(const bf16x8*)(kb0 + 32 * KSTR + 2 * 64 + ks * 32);
;       }
;     }
; #pragma unroll
;     for (int c = 0; c < NC2; ++c)
; #pragma unroll
;       for (int ks = 0; ks < 2; ++ks) {
;         s0 = MFMA(ka[c][ks], qf[c][ks], s0);
;         s1 = MFMA(kb[c][ks], qf[c][ks], s1);
;       }
;     if (NCH == 3) {
; #pragma unroll
;       for (int ks = 0; ks < 2; ++ks) {
;         s0 = MFMA(kc[ks], qf[NCH - 1][ks], s0);
;         s1 = MFMA(kd[ks], qf[NCH - 1][ks], s1);
;       }
;     }
;     if (MODE == 1) {
;       const float rel = (float)(qpos - t * 128 - hf * 64 - 4 * h);
; #pragma unroll
;       for (int i = 0; i < 16; ++i) {
;         const float ci = (float)((i & 3) + 8 * (i >> 2));
;         s0[i] -= slope2 * fabsf(rel - ci);
;         s1[i] -= slope2 * fabsf(rel - (ci + 32.f));
;       }
;     }
;     if (MODE == 2) {
;       const float* sbr = na.sb + (2 * t + hf - na.rq + 7) * 31;
; #pragma unroll
;       for (int i = 0; i < 16; ++i) {
;         const int kc0 = crow(i, h), kc1 = 32 + crow(i, h);
;         const int dc0 = min(max(kc0 - na.cq + 15, 0), 30), dc1 = min(max(kc1 - na.cq + 15, 0), 30);
;         const float b0 = sbr[dc0], b1 = sbr[dc1];
;         s0[i] = ((unsigned)(kc0 - na.c0) < 16u) ? s0[i] + b0 : -1e30f;
;         s1[i] = ((unsigned)(kc1 - na.c0) < 16u) ? s1[i] + b1 : -1e30f;
;       }
;     }
	ds_read_b128 v[48:51], v194 offset:9216
	ds_read_b128 v[196:199], v194 offset:9248
	ds_read_b128 v[52:55], v194 offset:13824
	ds_read_b128 v[200:203], v194 offset:13856
	ds_read_b128 v[204:207], v194 offset:9280
	ds_read_b128 v[208:211], v194 offset:9312
	ds_read_b128 v[218:221], v194 offset:13888
	ds_read_b128 v[222:225], v194 offset:13920
	s_waitcnt lgkmcnt(7)
	v_mfma_f32_32x32x16_bf16 v[64:79], v[48:51], v[84:87], 0
	ds_read_b32 v194, v193 offset:124
	v_mov_b32_e32 v193, 0xf149f2ca
	v_mov_b32_e32 v195, 0xf149f2ca
	s_waitcnt lgkmcnt(6)
	v_mfma_f32_32x32x16_bf16 v[48:63], v[52:55], v[84:87], 0
	v_mfma_f32_32x32x16_bf16 v[64:79], v[196:199], v[88:91], v[64:79]
	s_waitcnt lgkmcnt(5)
	v_mfma_f32_32x32x16_bf16 v[48:63], v[200:203], v[88:91], v[48:63]
	s_waitcnt lgkmcnt(4)
	v_mfma_f32_32x32x16_bf16 v[64:79], v[204:207], v[92:95], v[64:79]
	s_waitcnt lgkmcnt(2)
	v_mfma_f32_32x32x16_bf16 v[48:63], v[218:221], v[92:95], v[48:63]
	v_mfma_f32_32x32x16_bf16 v[64:79], v[208:211], v[96:99], v[64:79]
	s_waitcnt lgkmcnt(1)
	v_mfma_f32_32x32x16_bf16 v[48:63], v[222:225], v[96:99], v[48:63]
	v_add_u32_e32 v218, v192, v129
	ds_read_b32 v218, v218 offset:124
	v_add_u32_e32 v219, v192, v127
	ds_read_b32 v219, v219 offset:124
	v_add_u32_e32 v220, v192, v125
	ds_read_b32 v220, v220 offset:124
	v_add_u32_e32 v221, v192, v122
	ds_read_b32 v221, v221 offset:124
	v_add_u32_e32 v222, v192, v120
	ds_read_b32 v222, v222 offset:124
	v_add_u32_e32 v223, v192, v118
	ds_read_b32 v223, v223 offset:124
	v_add_u32_e32 v224, v192, v110
	ds_read_b32 v224, v224 offset:124
	v_add_u32_e32 v225, v192, v108
	ds_read_b32 v225, v225 offset:124
	s_waitcnt lgkmcnt(0)
	v_add_f32_e32 v218, v72, v218
	v_add_f32_e32 v219, v73, v219
	v_add_f32_e32 v220, v74, v220
	v_add_f32_e32 v221, v75, v221
	v_add_f32_e32 v222, v76, v222
	v_add_f32_e32 v223, v77, v223
	v_add_f32_e32 v224, v78, v224
	v_add_f32_e32 v225, v79, v225
	v_add_u32_e32 v195, v192, v190
	ds_read_b32 v195, v195 offset:124
	v_add_u32_e32 v193, v192, v188
	ds_read_b32 v193, v193 offset:124
	v_add_u32_e32 v196, v192, v186
	ds_read_b32 v196, v196 offset:124
	v_add_u32_e32 v78, v192, v184
	ds_read_b32 v78, v78 offset:124
	v_add_u32_e32 v197, v192, v182
	ds_read_b32 v197, v197 offset:124
	v_add_u32_e32 v79, v192, v135
	ds_read_b32 v79, v79 offset:124
	v_add_u32_e32 v72, v192, v133
	ds_read_b32 v72, v72 offset:124
	v_add_u32_e32 v73, v192, v131
	ds_read_b32 v73, v73 offset:124
	v_add_u32_e32 v198, v192, v189
	ds_read_b32 v198, v198 offset:124
	v_add_u32_e32 v199, v192, v187
	ds_read_b32 v199, v199 offset:124
	v_add_u32_e32 v200, v192, v185
	ds_read_b32 v200, v200 offset:124
	v_add_u32_e32 v201, v192, v183
	ds_read_b32 v201, v201 offset:124
	v_add_u32_e32 v202, v192, v181
	ds_read_b32 v202, v202 offset:124
	v_add_u32_e32 v203, v192, v134
	ds_read_b32 v203, v203 offset:124
	v_add_u32_e32 v204, v192, v132
	ds_read_b32 v204, v204 offset:124
	v_add_u32_e32 v205, v192, v130
	ds_read_b32 v205, v205 offset:124
	v_add_u32_e32 v206, v192, v128
	ds_read_b32 v206, v206 offset:124
	v_add_u32_e32 v207, v192, v126
	ds_read_b32 v207, v207 offset:124
	v_add_u32_e32 v208, v192, v124
	ds_read_b32 v208, v208 offset:124
	v_add_u32_e32 v209, v192, v121
	ds_read_b32 v209, v209 offset:124
	v_add_u32_e32 v76, v192, v119
	ds_read_b32 v76, v76 offset:124
	v_add_u32_e32 v210, v192, v111
	ds_read_b32 v210, v210 offset:124
	v_add_u32_e32 v77, v192, v109
	ds_read_b32 v77, v77 offset:124
	s_waitcnt lgkmcnt(0)
	v_add_f32_e32 v195, v64, v195
	v_add_f32_e32 v193, v65, v193
	v_add_f32_e32 v196, v66, v196
	v_add_f32_e32 v78, v67, v78
	v_add_f32_e32 v197, v68, v197
	v_add_f32_e32 v79, v69, v79
	v_add_f32_e32 v72, v70, v72
	v_add_f32_e32 v73, v71, v73
	v_mov_b32_e32 v166, 0xf149f2ca
	s_mov_b64 vcc, s[38:39]
	s_nop 0
	v_cndmask_b32_e32 v195, v166, v195, vcc
	s_mov_b64 vcc, s[42:43]
	s_nop 0
	v_cndmask_b32_e32 v193, v166, v193, vcc
	s_mov_b64 vcc, s[46:47]
	s_nop 0
	v_cndmask_b32_e32 v196, v166, v196, vcc
	s_mov_b64 vcc, s[54:55]
	s_nop 0
	v_cndmask_b32_e32 v197, v166, v197, vcc
	s_mov_b64 vcc, s[50:51]
	s_nop 0
	v_cndmask_b32_e32 v64, v166, v78, vcc
	s_mov_b64 vcc, s[58:59]
	s_nop 0
	v_cndmask_b32_e32 v67, v166, v79, vcc
	s_mov_b64 vcc, s[62:63]
	s_nop 0
	v_cndmask_b32_e32 v66, v166, v72, vcc
	s_mov_b64 vcc, s[66:67]
	s_nop 0
	v_cndmask_b32_e32 v65, v166, v73, vcc
	s_mov_b64 vcc, s[70:71]
	s_nop 0
	v_cndmask_b32_e32 v69, v166, v218, vcc
	s_mov_b64 vcc, s[74:75]
	s_nop 0
	v_cndmask_b32_e32 v68, v166, v219, vcc
	s_mov_b64 vcc, s[78:79]
	s_nop 0
	v_cndmask_b32_e32 v71, v166, v220, vcc
	s_mov_b64 vcc, s[82:83]
	s_nop 0
	v_cndmask_b32_e32 v70, v166, v221, vcc
	s_mov_b64 vcc, s[86:87]
	s_nop 0
	v_cndmask_b32_e32 v73, v166, v222, vcc
	s_mov_b64 vcc, s[90:91]
	s_nop 0
	v_cndmask_b32_e32 v72, v166, v223, vcc
	s_mov_b64 vcc, s[94:95]
	s_nop 0
	v_cndmask_b32_e32 v75, v166, v224, vcc
	s_mov_b64 vcc, s[0:1]
	s_nop 0
	v_cndmask_b32_e32 v74, v166, v225, vcc
	s_waitcnt lgkmcnt(14)
; #define MFMA(a, b, c) __builtin_amdgcn_mfma_f32_32x32x16_bf16((a), (b), (c), 0, 0, 0)
; DI float fexp2(float x) { return __builtin_amdgcn_exp2f(x); }
; DI float xhalf(float v) { return __shfl_xor(v, 32); }
; template <int NCH, int MODE, bool BOUND> ...
;     ...
;     if (BOUND) {
;       float ps = 0.f;
; #pragma unroll
;       for (int i = 0; i < 16; ++i) {
;         s0[i] = fexp2(s0[i]);
;         s1[i] = fexp2(s1[i]);
;         ps += s0[i] + s1[i];
;       }
;       l += ps;
;     } else {
;       float mx = fmaxf(s0[0], s1[0]);
; #pragma unroll
;       for (int i = 1; i < 16; ++i) mx = fmaxf(mx, fmaxf(s0[i], s1[i]));
;       mx = fmaxf(mx, xhalf(mx));
;       const float mnew = fmaxf(m, mx);
;       const float alpha = fexp2(m - mnew);
;       m = mnew;
;       float ps = 0.f;
; #pragma unroll
;       for (int i = 0; i < 16; ++i) {
;         s0[i] = fexp2(s0[i] - mnew);
;         s1[i] = fexp2(s1[i] - mnew);
;         ps += s0[i] + s1[i];
;       }
;       l = l * alpha + ps;
; #pragma unroll
;       for (int i = 0; i < 16; ++i) { o0[i] *= alpha; o1[i] *= alpha; }
;     }
;     const char* vb0 = cur + A_VOFF + r * V_ROW + hf * 128 + 16 * h;
; #pragma unroll
;     for (int kb = 0; kb < 2; ++kb)
; #pragma unroll
;       for (int s = 0; s < 2; ++s) {
;         uint4 pu;
;         if (kb == 0) {
;           pu.x = pk_bf16(s0[8 * s + 0], s0[8 * s + 1]); pu.y = pk_bf16(s0[8 * s + 2], s0[8 * s + 3]);
;           pu.z = pk_bf16(s0[8 * s + 4], s0[8 * s + 5]); pu.w = pk_bf16(s0[8 * s + 6], s0[8 * s + 7]);
;         } else {
;           pu.x = pk_bf16(s1[8 * s + 0], s1[8 * s + 1]); pu.y = pk_bf16(s1[8 * s + 2], s1[8 * s + 3]);
;           pu.z = pk_bf16(s1[8 * s + 4], s1[8 * s + 5]); pu.w = pk_bf16(s1[8 * s + 6], s1[8 * s + 7]);
;         }
;         const bf16x8 pf = __builtin_bit_cast(bf16x8, pu);
;         const int koff = (kb * 32 + 16 * s) * 2;
;         {
;           const bf16x8 vf = *(const bf16x8*)(vb0 + koff);
;           o0 = MFMA(vf, pf, o0);
;         }
;         {
;           const bf16x8 vf = *(const bf16x8*)(vb0 + 32 * V_ROW + koff);
;           o1 = MFMA(vf, pf, o1);
;         }
;       }
	v_add_f32_e32 v48, v48, v194
	v_add_f32_e32 v49, v49, v198
	v_cndmask_b32_e64 v48, v240, v48, s[40:41]
	s_waitcnt lgkmcnt(6)
	v_add_f32_e32 v57, v57, v206
	v_add_f32_e32 v51, v51, v200
	v_cndmask_b32_e64 v49, v240, v49, s[44:45]
	v_exp_f32_e32 v194, v195
	v_exp_f32_e32 v195, v48
	v_cndmask_b32_e64 v166, v240, v57, s[76:77]
	v_cndmask_b32_e64 v57, v240, v51, s[52:53]
	v_exp_f32_e32 v51, v193
	v_exp_f32_e32 v49, v49
	s_waitcnt lgkmcnt(1)
	v_add_f32_e32 v62, v62, v210
	v_add_f32_e32 v56, v56, v205
	v_add_f32_e32 v52, v52, v201
	v_add_f32_e32 v50, v50, v199
	v_cndmask_b32_e64 v78, v240, v62, s[96:97]
	v_cndmask_b32_e64 v62, v240, v56, s[72:73]
	v_cndmask_b32_e64 v56, v240, v52, s[56:57]
	v_cndmask_b32_e64 v52, v240, v50, s[48:49]
	s_waitcnt lgkmcnt(0)
	v_add_f32_e32 v50, v63, v77
	v_add_f32_e32 v58, v58, v207
	v_add_f32_e32 v55, v55, v204
	v_add_f32_e32 v54, v54, v203
	v_cndmask_b32_e64 v77, v240, v50, s[4:5]
	v_add_f32_e32 v48, v195, v194
	v_mov_b32_e32 v50, v1
	v_add_f32_e32 v59, v59, v208
	v_cndmask_b32_e64 v79, v240, v58, s[80:81]
	v_cndmask_b32_e64 v167, v240, v55, s[68:69]
	v_cndmask_b32_e64 v58, v240, v54, s[64:65]
	v_add_f32_e32 v53, v53, v202
	v_pk_add_f32 v[54:55], v[48:49], v[50:51]
	v_exp_f32_e32 v48, v196
	v_exp_f32_e32 v193, v52
	v_exp_f32_e32 v196, v57
	v_add_f32_e32 v61, v61, v76
	v_cndmask_b32_e64 v76, v240, v59, s[84:85]
	v_cndmask_b32_e64 v59, v240, v53, s[60:61]
	v_exp_f32_e32 v53, v64
	v_pk_add_f32 v[54:55], v[54:55], v[54:55] op_sel:[0,1] op_sel_hi:[1,0]
	v_add_f32_e32 v52, v193, v48
	v_mov_b32_e32 v55, v196
	v_pk_add_f32 v[54:55], v[54:55], v[52:53]
	v_exp_f32_e32 v52, v197
	v_exp_f32_e32 v197, v56
	v_exp_f32_e32 v198, v59
	v_exp_f32_e32 v57, v67
	v_pk_add_f32 v[54:55], v[54:55], v[54:55] op_sel:[0,1] op_sel_hi:[1,0]
	v_add_f32_e32 v56, v197, v52
	v_mov_b32_e32 v55, v198
	v_pk_add_f32 v[54:55], v[54:55], v[56:57]
	v_exp_f32_e32 v56, v66
	v_exp_f32_e32 v199, v58
	v_exp_f32_e32 v167, v167
	v_exp_f32_e32 v59, v65
	v_pk_add_f32 v[54:55], v[54:55], v[54:55] op_sel:[0,1] op_sel_hi:[1,0]
	v_exp_f32_e32 v200, v69
	v_exp_f32_e32 v201, v62
	v_exp_f32_e32 v166, v166
	v_add_f32_e32 v58, v199, v56
	v_mov_b32_e32 v55, v167
	v_exp_f32_e32 v63, v68
	v_pk_add_f32 v[54:55], v[54:55], v[58:59]
	v_add_f32_e32 v62, v201, v200
	v_pk_add_f32 v[54:55], v[54:55], v[54:55] op_sel:[0,1] op_sel_hi:[1,0]
	v_exp_f32_e32 v65, v70
	v_mov_b32_e32 v55, v166
	v_pk_add_f32 v[54:55], v[54:55], v[62:63]
	v_exp_f32_e32 v62, v71
	v_exp_f32_e32 v71, v79
	v_exp_f32_e32 v70, v76
	v_add_f32_e32 v60, v60, v209
	v_pk_add_f32 v[54:55], v[54:55], v[54:55] op_sel:[0,1] op_sel_hi:[1,0]
	v_cndmask_b32_e64 v61, v240, v61, s[92:93]
	v_cndmask_b32_e64 v60, v240, v60, s[88:89]
	v_add_f32_e32 v64, v71, v62
	v_mov_b32_e32 v55, v70
	v_pk_add_f32 v[54:55], v[54:55], v[64:65]
	v_exp_f32_e32 v64, v73
	v_exp_f32_e32 v73, v60
	v_exp_f32_e32 v67, v72
	v_exp_f32_e32 v72, v61
	v_pk_add_f32 v[54:55], v[54:55], v[54:55] op_sel:[0,1] op_sel_hi:[1,0]
	v_add_f32_e32 v66, v73, v64
	v_exp_f32_e32 v69, v74
	v_mov_b32_e32 v55, v72
	v_pk_add_f32 v[54:55], v[54:55], v[66:67]
	v_exp_f32_e32 v66, v75
	v_exp_f32_e32 v75, v78
	v_exp_f32_e32 v74, v77
	v_pk_add_f32 v[54:55], v[54:55], v[54:55] op_sel:[0,1] op_sel_hi:[1,0]
	v_cvt_pk_bf16_f32 v52, v52, v57
	v_add_f32_e32 v68, v75, v66
	v_mov_b32_e32 v55, v74
	v_pk_add_f32 v[54:55], v[54:55], v[68:69]
	v_add3_u32 v68, s31, v107, v0
	v_add_f32_e32 v50, v54, v55
	v_add_f32_e32 v123, v123, v50
	v_cvt_pk_bf16_f32 v50, v194, v51
	v_cvt_pk_bf16_f32 v51, v48, v53
	v_cvt_pk_bf16_f32 v53, v56, v59
	ds_read_b128 v[54:57], v68 offset:26752
	ds_read_b128 v[58:61], v68 offset:26784
	s_waitcnt lgkmcnt(1)
	v_mfma_f32_32x32x16_bf16 v[32:47], v[54:57], v[50:53], v[32:47]
	ds_read_b128 v[54:57], v68 offset:35456
	v_cvt_pk_bf16_f32 v48, v195, v49
	v_cvt_pk_bf16_f32 v49, v193, v196
	s_waitcnt lgkmcnt(0)
	v_mfma_f32_32x32x16_bf16 v[16:31], v[54:57], v[50:53], v[16:31]
	ds_read_b128 v[54:57], v68 offset:35488
	v_cvt_pk_bf16_f32 v50, v200, v63
	v_cvt_pk_bf16_f32 v51, v62, v65
	v_cvt_pk_bf16_f32 v52, v64, v67
	v_cvt_pk_bf16_f32 v53, v66, v69
	s_nop 1
	v_mfma_f32_32x32x16_bf16 v[32:47], v[58:61], v[50:53], v[32:47]
	s_waitcnt lgkmcnt(0)
	v_mfma_f32_32x32x16_bf16 v[16:31], v[54:57], v[50:53], v[16:31]
	ds_read_b128 v[52:55], v68 offset:26816
	v_cvt_pk_bf16_f32 v50, v197, v198
	v_cvt_pk_bf16_f32 v51, v199, v167
	s_waitcnt lgkmcnt(0)
	s_nop 0
	v_mfma_f32_32x32x16_bf16 v[32:47], v[52:55], v[48:51], v[32:47]
	ds_read_b128 v[52:55], v68 offset:35520
	s_waitcnt lgkmcnt(0)
	v_mfma_f32_32x32x16_bf16 v[16:31], v[52:55], v[48:51], v[16:31]
	ds_read_b128 v[52:55], v68 offset:26848
	v_cvt_pk_bf16_f32 v48, v201, v166
	v_cvt_pk_bf16_f32 v49, v71, v70
	v_cvt_pk_bf16_f32 v50, v73, v72
	v_cvt_pk_bf16_f32 v51, v75, v74
	s_waitcnt lgkmcnt(0)
	s_nop 0
	v_mfma_f32_32x32x16_bf16 v[32:47], v[52:55], v[48:51], v[32:47]
	ds_read_b128 v[52:55], v68 offset:35552
	s_waitcnt lgkmcnt(0)
	v_mfma_f32_32x32x16_bf16 v[16:31], v[52:55], v[48:51], v[16:31]

; DI float bf_lo(unsigned u) { return __uint_as_float(u << 16); }
; DI float bf_hi(unsigned u) { return __uint_as_float(u & 0xffff0000u); }
; DI float frsq(float x) { return __builtin_amdgcn_rsqf(x); }
; DI float xhalf(float v) { return __shfl_xor(v, 32); }
; DI void phase_attn(const Params& p, int layer, char* smem) {
;     ...
;       ssq += xhalf(ssq);
;       const float rstd = frsq(ssq * (1.f / 256.f) + EPS);
; #pragma unroll
;       for (int j = 0; j < 32; ++j) {
;         uint2* a = (uint2*)(ocat + (size_t)qtok * 1024 + 768 + 8 * j + 4 * h);
;         uint2 u = *a;
;         u.x = pk_bf16(bf_lo(u.x) * rstd, bf_hi(u.x) * rstd);
;         u.y = pk_bf16(bf_lo(u.y) * rstd, bf_hi(u.y) * rstd);
;         *a = u;
;       }
.LBB0_288:
	global_load_dwordx2 v[10:11], v[112:113], off offset:1536
	global_load_dwordx2 v[12:13], v[112:113], off offset:1552
	global_load_dwordx2 v[14:15], v[112:113], off offset:1568
	global_load_dwordx2 v[16:17], v[112:113], off offset:1584
	global_load_dwordx2 v[18:19], v[112:113], off offset:1600
	global_load_dwordx2 v[20:21], v[112:113], off offset:1616
	global_load_dwordx2 v[22:23], v[112:113], off offset:1632
	global_load_dwordx2 v[24:25], v[112:113], off offset:1648
	global_load_dwordx2 v[26:27], v[112:113], off offset:1664
	global_load_dwordx2 v[28:29], v[112:113], off offset:1680
	global_load_dwordx2 v[30:31], v[112:113], off offset:1696
	global_load_dwordx2 v[32:33], v[112:113], off offset:1712
	global_load_dwordx2 v[34:35], v[112:113], off offset:1728
	global_load_dwordx2 v[36:37], v[112:113], off offset:1744
	global_load_dwordx2 v[38:39], v[112:113], off offset:1760
	global_load_dwordx2 v[40:41], v[112:113], off offset:1776
	global_load_dwordx2 v[42:43], v[112:113], off offset:1792
	global_load_dwordx2 v[44:45], v[112:113], off offset:1808
	global_load_dwordx2 v[46:47], v[112:113], off offset:1824
	global_load_dwordx2 v[48:49], v[112:113], off offset:1840
	global_load_dwordx2 v[50:51], v[112:113], off offset:1856
	global_load_dwordx2 v[52:53], v[112:113], off offset:1872
	global_load_dwordx2 v[54:55], v[112:113], off offset:1888
	global_load_dwordx2 v[56:57], v[112:113], off offset:1904
	global_load_dwordx2 v[58:59], v[112:113], off offset:1920
	global_load_dwordx2 v[60:61], v[112:113], off offset:1936
	global_load_dwordx2 v[62:63], v[112:113], off offset:1952
	global_load_dwordx2 v[64:65], v[112:113], off offset:1968
	global_load_dwordx2 v[66:67], v[112:113], off offset:1984
	global_load_dwordx2 v[68:69], v[112:113], off offset:2000
	global_load_dwordx2 v[70:71], v[112:113], off offset:2016
	global_load_dwordx2 v[72:73], v[112:113], off offset:2032
	ds_bpermute_b32 v0, v180, v179
	s_mov_b64 s[0:1], 0
	v_readlane_b32 s44, v255, 20
	v_readlane_b32 s8, v255, 21
	s_waitcnt lgkmcnt(0)
	v_add_f32_e32 v0, v179, v0
	v_fmamk_f32 v0, v0, 0x3b800000, v229
	v_rsq_f32_e32 v0, v0
	s_waitcnt vmcnt(31)
	v_lshlrev_b32_e32 v4, 16, v10
	v_and_b32_e32 v5, 0xffff0000, v10
	v_pk_mul_f32 v[4:5], v[0:1], v[4:5] op_sel_hi:[0,1]
	v_cvt_pk_bf16_f32 v10, v4, v5
	v_lshlrev_b32_e32 v4, 16, v11
	v_and_b32_e32 v5, 0xffff0000, v11
	v_pk_mul_f32 v[4:5], v[0:1], v[4:5] op_sel_hi:[0,1]
	v_cvt_pk_bf16_f32 v11, v4, v5
	global_store_dwordx2 v[112:113], v[10:11], off offset:1536
	s_waitcnt vmcnt(31)
	v_lshlrev_b32_e32 v4, 16, v12
	v_and_b32_e32 v5, 0xffff0000, v12
	v_pk_mul_f32 v[4:5], v[0:1], v[4:5] op_sel_hi:[0,1]
	v_cvt_pk_bf16_f32 v12, v4, v5
	v_lshlrev_b32_e32 v4, 16, v13
	v_and_b32_e32 v5, 0xffff0000, v13
	v_pk_mul_f32 v[4:5], v[0:1], v[4:5] op_sel_hi:[0,1]
	v_cvt_pk_bf16_f32 v13, v4, v5
	global_store_dwordx2 v[112:113], v[12:13], off offset:1552
	s_waitcnt vmcnt(31)
	v_lshlrev_b32_e32 v4, 16, v14
	v_and_b32_e32 v5, 0xffff0000, v14
	v_pk_mul_f32 v[4:5], v[0:1], v[4:5] op_sel_hi:[0,1]
	v_cvt_pk_bf16_f32 v14, v4, v5
	v_lshlrev_b32_e32 v4, 16, v15
	v_and_b32_e32 v5, 0xffff0000, v15
	v_pk_mul_f32 v[4:5], v[0:1], v[4:5] op_sel_hi:[0,1]
	v_cvt_pk_bf16_f32 v15, v4, v5
	global_store_dwordx2 v[112:113], v[14:15], off offset:1568
	s_waitcnt vmcnt(31)
	v_lshlrev_b32_e32 v4, 16, v16
	v_and_b32_e32 v5, 0xffff0000, v16
	v_pk_mul_f32 v[4:5], v[0:1], v[4:5] op_sel_hi:[0,1]
	v_cvt_pk_bf16_f32 v16, v4, v5
	v_lshlrev_b32_e32 v4, 16, v17
	v_and_b32_e32 v5, 0xffff0000, v17
	v_pk_mul_f32 v[4:5], v[0:1], v[4:5] op_sel_hi:[0,1]
	v_cvt_pk_bf16_f32 v17, v4, v5
	global_store_dwordx2 v[112:113], v[16:17], off offset:1584
	s_waitcnt vmcnt(31)
	v_lshlrev_b32_e32 v4, 16, v18
	v_and_b32_e32 v5, 0xffff0000, v18
	v_pk_mul_f32 v[4:5], v[0:1], v[4:5] op_sel_hi:[0,1]
	v_cvt_pk_bf16_f32 v18, v4, v5
	v_lshlrev_b32_e32 v4, 16, v19
	v_and_b32_e32 v5, 0xffff0000, v19
	v_pk_mul_f32 v[4:5], v[0:1], v[4:5] op_sel_hi:[0,1]
	v_cvt_pk_bf16_f32 v19, v4, v5
	global_store_dwordx2 v[112:113], v[18:19], off offset:1600
	s_waitcnt vmcnt(31)
	v_lshlrev_b32_e32 v4, 16, v20
	v_and_b32_e32 v5, 0xffff0000, v20
	v_pk_mul_f32 v[4:5], v[0:1], v[4:5] op_sel_hi:[0,1]
	v_cvt_pk_bf16_f32 v20, v4, v5
	v_lshlrev_b32_e32 v4, 16, v21
	v_and_b32_e32 v5, 0xffff0000, v21
	v_pk_mul_f32 v[4:5], v[0:1], v[4:5] op_sel_hi:[0,1]
	v_cvt_pk_bf16_f32 v21, v4, v5
	global_store_dwordx2 v[112:113], v[20:21], off offset:1616
	s_waitcnt vmcnt(31)
	v_lshlrev_b32_e32 v4, 16, v22
	v_and_b32_e32 v5, 0xffff0000, v22
	v_pk_mul_f32 v[4:5], v[0:1], v[4:5] op_sel_hi:[0,1]
	v_cvt_pk_bf16_f32 v22, v4, v5
	v_lshlrev_b32_e32 v4, 16, v23
	v_and_b32_e32 v5, 0xffff0000, v23
	v_pk_mul_f32 v[4:5], v[0:1], v[4:5] op_sel_hi:[0,1]
	v_cvt_pk_bf16_f32 v23, v4, v5
	global_store_dwordx2 v[112:113], v[22:23], off offset:1632
	s_waitcnt vmcnt(31)
	v_lshlrev_b32_e32 v4, 16, v24
	v_and_b32_e32 v5, 0xffff0000, v24
	v_pk_mul_f32 v[4:5], v[0:1], v[4:5] op_sel_hi:[0,1]
	v_cvt_pk_bf16_f32 v24, v4, v5
	v_lshlrev_b32_e32 v4, 16, v25
	v_and_b32_e32 v5, 0xffff0000, v25
	v_pk_mul_f32 v[4:5], v[0:1], v[4:5] op_sel_hi:[0,1]
	v_cvt_pk_bf16_f32 v25, v4, v5
	global_store_dwordx2 v[112:113], v[24:25], off offset:1648
	s_waitcnt vmcnt(31)
	v_lshlrev_b32_e32 v4, 16, v26
	v_and_b32_e32 v5, 0xffff0000, v26
	v_pk_mul_f32 v[4:5], v[0:1], v[4:5] op_sel_hi:[0,1]
	v_cvt_pk_bf16_f32 v26, v4, v5
	v_lshlrev_b32_e32 v4, 16, v27
	v_and_b32_e32 v5, 0xffff0000, v27
	v_pk_mul_f32 v[4:5], v[0:1], v[4:5] op_sel_hi:[0,1]
	v_cvt_pk_bf16_f32 v27, v4, v5
	global_store_dwordx2 v[112:113], v[26:27], off offset:1664
	s_waitcnt vmcnt(31)
; DI float bf_lo(unsigned u) { return __uint_as_float(u << 16); }
; DI float bf_hi(unsigned u) { return __uint_as_float(u & 0xffff0000u); }
; DI void phase_attn(const Params& p, int layer, char* smem) {
;     ...
;       for (int j = 0; j < 32; ++j) {
;         uint2* a = (uint2*)(ocat + (size_t)qtok * 1024 + 768 + 8 * j + 4 * h);
;         uint2 u = *a;
;         u.x = pk_bf16(bf_lo(u.x) * rstd, bf_hi(u.x) * rstd);
;         u.y = pk_bf16(bf_lo(u.y) * rstd, bf_hi(u.y) * rstd);
;         *a = u;
;       }
	v_lshlrev_b32_e32 v4, 16, v28
	v_and_b32_e32 v5, 0xffff0000, v28
	v_pk_mul_f32 v[4:5], v[0:1], v[4:5] op_sel_hi:[0,1]
	v_cvt_pk_bf16_f32 v28, v4, v5
	v_lshlrev_b32_e32 v4, 16, v29
	v_and_b32_e32 v5, 0xffff0000, v29
	v_pk_mul_f32 v[4:5], v[0:1], v[4:5] op_sel_hi:[0,1]
	v_cvt_pk_bf16_f32 v29, v4, v5
	global_store_dwordx2 v[112:113], v[28:29], off offset:1680
	s_waitcnt vmcnt(31)
	v_lshlrev_b32_e32 v4, 16, v30
	v_and_b32_e32 v5, 0xffff0000, v30
	v_pk_mul_f32 v[4:5], v[0:1], v[4:5] op_sel_hi:[0,1]
	v_cvt_pk_bf16_f32 v30, v4, v5
	v_lshlrev_b32_e32 v4, 16, v31
	v_and_b32_e32 v5, 0xffff0000, v31
	v_pk_mul_f32 v[4:5], v[0:1], v[4:5] op_sel_hi:[0,1]
	v_cvt_pk_bf16_f32 v31, v4, v5
	global_store_dwordx2 v[112:113], v[30:31], off offset:1696
	s_waitcnt vmcnt(31)
	v_lshlrev_b32_e32 v4, 16, v32
	v_and_b32_e32 v5, 0xffff0000, v32
	v_pk_mul_f32 v[4:5], v[0:1], v[4:5] op_sel_hi:[0,1]
	v_cvt_pk_bf16_f32 v32, v4, v5
	v_lshlrev_b32_e32 v4, 16, v33
	v_and_b32_e32 v5, 0xffff0000, v33
	v_pk_mul_f32 v[4:5], v[0:1], v[4:5] op_sel_hi:[0,1]
	v_cvt_pk_bf16_f32 v33, v4, v5
	global_store_dwordx2 v[112:113], v[32:33], off offset:1712
	s_waitcnt vmcnt(31)
	v_lshlrev_b32_e32 v4, 16, v34
	v_and_b32_e32 v5, 0xffff0000, v34
	v_pk_mul_f32 v[4:5], v[0:1], v[4:5] op_sel_hi:[0,1]
	v_cvt_pk_bf16_f32 v34, v4, v5
	v_lshlrev_b32_e32 v4, 16, v35
	v_and_b32_e32 v5, 0xffff0000, v35
	v_pk_mul_f32 v[4:5], v[0:1], v[4:5] op_sel_hi:[0,1]
	v_cvt_pk_bf16_f32 v35, v4, v5
	global_store_dwordx2 v[112:113], v[34:35], off offset:1728
	s_waitcnt vmcnt(31)
	v_lshlrev_b32_e32 v4, 16, v36
	v_and_b32_e32 v5, 0xffff0000, v36
	v_pk_mul_f32 v[4:5], v[0:1], v[4:5] op_sel_hi:[0,1]
	v_cvt_pk_bf16_f32 v36, v4, v5
	v_lshlrev_b32_e32 v4, 16, v37
	v_and_b32_e32 v5, 0xffff0000, v37
	v_pk_mul_f32 v[4:5], v[0:1], v[4:5] op_sel_hi:[0,1]
	v_cvt_pk_bf16_f32 v37, v4, v5
	global_store_dwordx2 v[112:113], v[36:37], off offset:1744
	s_waitcnt vmcnt(31)
	v_lshlrev_b32_e32 v4, 16, v38
	v_and_b32_e32 v5, 0xffff0000, v38
	v_pk_mul_f32 v[4:5], v[0:1], v[4:5] op_sel_hi:[0,1]
	v_cvt_pk_bf16_f32 v38, v4, v5
	v_lshlrev_b32_e32 v4, 16, v39
	v_and_b32_e32 v5, 0xffff0000, v39
	v_pk_mul_f32 v[4:5], v[0:1], v[4:5] op_sel_hi:[0,1]
	v_cvt_pk_bf16_f32 v39, v4, v5
	global_store_dwordx2 v[112:113], v[38:39], off offset:1760
	s_waitcnt vmcnt(31)
	v_lshlrev_b32_e32 v4, 16, v40
	v_and_b32_e32 v5, 0xffff0000, v40
	v_pk_mul_f32 v[4:5], v[0:1], v[4:5] op_sel_hi:[0,1]
	v_cvt_pk_bf16_f32 v40, v4, v5
	v_lshlrev_b32_e32 v4, 16, v41
	v_and_b32_e32 v5, 0xffff0000, v41
	v_pk_mul_f32 v[4:5], v[0:1], v[4:5] op_sel_hi:[0,1]
	v_cvt_pk_bf16_f32 v41, v4, v5
	global_store_dwordx2 v[112:113], v[40:41], off offset:1776
	s_waitcnt vmcnt(31)
	v_lshlrev_b32_e32 v4, 16, v42
	v_and_b32_e32 v5, 0xffff0000, v42
	v_pk_mul_f32 v[4:5], v[0:1], v[4:5] op_sel_hi:[0,1]
	v_cvt_pk_bf16_f32 v42, v4, v5
	v_lshlrev_b32_e32 v4, 16, v43
	v_and_b32_e32 v5, 0xffff0000, v43
	v_pk_mul_f32 v[4:5], v[0:1], v[4:5] op_sel_hi:[0,1]
	v_cvt_pk_bf16_f32 v43, v4, v5
	global_store_dwordx2 v[112:113], v[42:43], off offset:1792
	s_waitcnt vmcnt(31)
	v_lshlrev_b32_e32 v4, 16, v44
	v_and_b32_e32 v5, 0xffff0000, v44
	v_pk_mul_f32 v[4:5], v[0:1], v[4:5] op_sel_hi:[0,1]
	v_cvt_pk_bf16_f32 v44, v4, v5
	v_lshlrev_b32_e32 v4, 16, v45
	v_and_b32_e32 v5, 0xffff0000, v45
	v_pk_mul_f32 v[4:5], v[0:1], v[4:5] op_sel_hi:[0,1]
	v_cvt_pk_bf16_f32 v45, v4, v5
	global_store_dwordx2 v[112:113], v[44:45], off offset:1808
	s_waitcnt vmcnt(31)
	v_lshlrev_b32_e32 v4, 16, v46
	v_and_b32_e32 v5, 0xffff0000, v46
	v_pk_mul_f32 v[4:5], v[0:1], v[4:5] op_sel_hi:[0,1]
	v_cvt_pk_bf16_f32 v46, v4, v5
	v_lshlrev_b32_e32 v4, 16, v47
	v_and_b32_e32 v5, 0xffff0000, v47
	v_pk_mul_f32 v[4:5], v[0:1], v[4:5] op_sel_hi:[0,1]
	v_cvt_pk_bf16_f32 v47, v4, v5
	global_store_dwordx2 v[112:113], v[46:47], off offset:1824
	s_waitcnt vmcnt(31)
	v_lshlrev_b32_e32 v4, 16, v48
	v_and_b32_e32 v5, 0xffff0000, v48
	v_pk_mul_f32 v[4:5], v[0:1], v[4:5] op_sel_hi:[0,1]
	v_cvt_pk_bf16_f32 v48, v4, v5
	v_lshlrev_b32_e32 v4, 16, v49
	v_and_b32_e32 v5, 0xffff0000, v49
	v_pk_mul_f32 v[4:5], v[0:1], v[4:5] op_sel_hi:[0,1]
	v_cvt_pk_bf16_f32 v49, v4, v5
	global_store_dwordx2 v[112:113], v[48:49], off offset:1840
	s_waitcnt vmcnt(31)
; DI float bf_lo(unsigned u) { return __uint_as_float(u << 16); }
; DI float bf_hi(unsigned u) { return __uint_as_float(u & 0xffff0000u); }
; DI void phase_attn(const Params& p, int layer, char* smem) {
;     ...
;       for (int j = 0; j < 32; ++j) {
;         uint2* a = (uint2*)(ocat + (size_t)qtok * 1024 + 768 + 8 * j + 4 * h);
;         uint2 u = *a;
;         u.x = pk_bf16(bf_lo(u.x) * rstd, bf_hi(u.x) * rstd);
;         u.y = pk_bf16(bf_lo(u.y) * rstd, bf_hi(u.y) * rstd);
;         *a = u;
;       }
	v_lshlrev_b32_e32 v4, 16, v50
	v_and_b32_e32 v5, 0xffff0000, v50
	v_pk_mul_f32 v[4:5], v[0:1], v[4:5] op_sel_hi:[0,1]
	v_cvt_pk_bf16_f32 v50, v4, v5
	v_lshlrev_b32_e32 v4, 16, v51
	v_and_b32_e32 v5, 0xffff0000, v51
	v_pk_mul_f32 v[4:5], v[0:1], v[4:5] op_sel_hi:[0,1]
	v_cvt_pk_bf16_f32 v51, v4, v5
	global_store_dwordx2 v[112:113], v[50:51], off offset:1856
	s_waitcnt vmcnt(31)
	v_lshlrev_b32_e32 v4, 16, v52
	v_and_b32_e32 v5, 0xffff0000, v52
	v_pk_mul_f32 v[4:5], v[0:1], v[4:5] op_sel_hi:[0,1]
	v_cvt_pk_bf16_f32 v52, v4, v5
	v_lshlrev_b32_e32 v4, 16, v53
	v_and_b32_e32 v5, 0xffff0000, v53
	v_pk_mul_f32 v[4:5], v[0:1], v[4:5] op_sel_hi:[0,1]
	v_cvt_pk_bf16_f32 v53, v4, v5
	global_store_dwordx2 v[112:113], v[52:53], off offset:1872
	s_waitcnt vmcnt(31)
	v_lshlrev_b32_e32 v4, 16, v54
	v_and_b32_e32 v5, 0xffff0000, v54
	v_pk_mul_f32 v[4:5], v[0:1], v[4:5] op_sel_hi:[0,1]
	v_cvt_pk_bf16_f32 v54, v4, v5
	v_lshlrev_b32_e32 v4, 16, v55
	v_and_b32_e32 v5, 0xffff0000, v55
	v_pk_mul_f32 v[4:5], v[0:1], v[4:5] op_sel_hi:[0,1]
	v_cvt_pk_bf16_f32 v55, v4, v5
	global_store_dwordx2 v[112:113], v[54:55], off offset:1888
	s_waitcnt vmcnt(31)
	v_lshlrev_b32_e32 v4, 16, v56
	v_and_b32_e32 v5, 0xffff0000, v56
	v_pk_mul_f32 v[4:5], v[0:1], v[4:5] op_sel_hi:[0,1]
	v_cvt_pk_bf16_f32 v56, v4, v5
	v_lshlrev_b32_e32 v4, 16, v57
	v_and_b32_e32 v5, 0xffff0000, v57
	v_pk_mul_f32 v[4:5], v[0:1], v[4:5] op_sel_hi:[0,1]
	v_cvt_pk_bf16_f32 v57, v4, v5
	global_store_dwordx2 v[112:113], v[56:57], off offset:1904
	s_waitcnt vmcnt(31)
	v_lshlrev_b32_e32 v4, 16, v58
	v_and_b32_e32 v5, 0xffff0000, v58
	v_pk_mul_f32 v[4:5], v[0:1], v[4:5] op_sel_hi:[0,1]
	v_cvt_pk_bf16_f32 v58, v4, v5
	v_lshlrev_b32_e32 v4, 16, v59
	v_and_b32_e32 v5, 0xffff0000, v59
	v_pk_mul_f32 v[4:5], v[0:1], v[4:5] op_sel_hi:[0,1]
	v_cvt_pk_bf16_f32 v59, v4, v5
	global_store_dwordx2 v[112:113], v[58:59], off offset:1920
	s_waitcnt vmcnt(31)
	v_lshlrev_b32_e32 v4, 16, v60
	v_and_b32_e32 v5, 0xffff0000, v60
	v_pk_mul_f32 v[4:5], v[0:1], v[4:5] op_sel_hi:[0,1]
	v_cvt_pk_bf16_f32 v60, v4, v5
	v_lshlrev_b32_e32 v4, 16, v61
	v_and_b32_e32 v5, 0xffff0000, v61
	v_pk_mul_f32 v[4:5], v[0:1], v[4:5] op_sel_hi:[0,1]
	v_cvt_pk_bf16_f32 v61, v4, v5
	global_store_dwordx2 v[112:113], v[60:61], off offset:1936
	s_waitcnt vmcnt(31)
	v_lshlrev_b32_e32 v4, 16, v62
	v_and_b32_e32 v5, 0xffff0000, v62
	v_pk_mul_f32 v[4:5], v[0:1], v[4:5] op_sel_hi:[0,1]
	v_cvt_pk_bf16_f32 v62, v4, v5
	v_lshlrev_b32_e32 v4, 16, v63
	v_and_b32_e32 v5, 0xffff0000, v63
	v_pk_mul_f32 v[4:5], v[0:1], v[4:5] op_sel_hi:[0,1]
	v_cvt_pk_bf16_f32 v63, v4, v5
	global_store_dwordx2 v[112:113], v[62:63], off offset:1952
	s_waitcnt vmcnt(31)
	v_lshlrev_b32_e32 v4, 16, v64
	v_and_b32_e32 v5, 0xffff0000, v64
	v_pk_mul_f32 v[4:5], v[0:1], v[4:5] op_sel_hi:[0,1]
	v_cvt_pk_bf16_f32 v64, v4, v5
	v_lshlrev_b32_e32 v4, 16, v65
	v_and_b32_e32 v5, 0xffff0000, v65
	v_pk_mul_f32 v[4:5], v[0:1], v[4:5] op_sel_hi:[0,1]
	v_cvt_pk_bf16_f32 v65, v4, v5
	global_store_dwordx2 v[112:113], v[64:65], off offset:1968
	s_waitcnt vmcnt(31)
	v_lshlrev_b32_e32 v4, 16, v66
	v_and_b32_e32 v5, 0xffff0000, v66
	v_pk_mul_f32 v[4:5], v[0:1], v[4:5] op_sel_hi:[0,1]
	v_cvt_pk_bf16_f32 v66, v4, v5
	v_lshlrev_b32_e32 v4, 16, v67
	v_and_b32_e32 v5, 0xffff0000, v67
	v_pk_mul_f32 v[4:5], v[0:1], v[4:5] op_sel_hi:[0,1]
	v_cvt_pk_bf16_f32 v67, v4, v5
	global_store_dwordx2 v[112:113], v[66:67], off offset:1984
	s_waitcnt vmcnt(31)
	v_lshlrev_b32_e32 v4, 16, v68
	v_and_b32_e32 v5, 0xffff0000, v68
	v_pk_mul_f32 v[4:5], v[0:1], v[4:5] op_sel_hi:[0,1]
	v_cvt_pk_bf16_f32 v68, v4, v5
	v_lshlrev_b32_e32 v4, 16, v69
	v_and_b32_e32 v5, 0xffff0000, v69
	v_pk_mul_f32 v[4:5], v[0:1], v[4:5] op_sel_hi:[0,1]
	v_cvt_pk_bf16_f32 v69, v4, v5
	global_store_dwordx2 v[112:113], v[68:69], off offset:2000
	s_waitcnt vmcnt(31)
	v_lshlrev_b32_e32 v4, 16, v70
	v_and_b32_e32 v5, 0xffff0000, v70
	v_pk_mul_f32 v[4:5], v[0:1], v[4:5] op_sel_hi:[0,1]
	v_cvt_pk_bf16_f32 v70, v4, v5
	v_lshlrev_b32_e32 v4, 16, v71
	v_and_b32_e32 v5, 0xffff0000, v71
	v_pk_mul_f32 v[4:5], v[0:1], v[4:5] op_sel_hi:[0,1]
	v_cvt_pk_bf16_f32 v71, v4, v5
	global_store_dwordx2 v[112:113], v[70:71], off offset:2016
	s_waitcnt vmcnt(31)
	v_lshlrev_b32_e32 v4, 16, v72
	v_and_b32_e32 v5, 0xffff0000, v72
	v_pk_mul_f32 v[4:5], v[0:1], v[4:5] op_sel_hi:[0,1]
	v_cvt_pk_bf16_f32 v72, v4, v5
	v_lshlrev_b32_e32 v4, 16, v73
	v_and_b32_e32 v5, 0xffff0000, v73
	v_pk_mul_f32 v[4:5], v[0:1], v[4:5] op_sel_hi:[0,1]
	v_cvt_pk_bf16_f32 v73, v4, v5
	global_store_dwordx2 v[112:113], v[72:73], off offset:2032

; DI float bf_lo(unsigned u) { return __uint_as_float(u << 16); }
; DI float bf_hi(unsigned u) { return __uint_as_float(u & 0xffff0000u); }
; DI float frsq(float x) { return __builtin_amdgcn_rsqf(x); }
; DI float xhalf(float v) { return __shfl_xor(v, 32); }
; DI void phase_attn(const Params& p, int layer, char* smem) {
;     ...
;       ssq += xhalf(ssq);
;       const float rstd = frsq(ssq * (1.f / 256.f) + EPS);
; #pragma unroll
;       for (int j = 0; j < 32; ++j) {
;         uint2* a = (uint2*)(ocat + (size_t)qtok * 1024 + 8 * j + 4 * h);
;         uint2 u = *a;
;         u.x = pk_bf16(bf_lo(u.x) * rstd, bf_hi(u.x) * rstd);
;         u.y = pk_bf16(bf_lo(u.y) * rstd, bf_hi(u.y) * rstd);
;         *a = u;
;       }
.LBB0_345:
	ds_bpermute_b32 v0, v206, v147
	v_lshlrev_b64 v[4:5], 11, v[148:149]
	v_lshl_add_u64 v[4:5], s[66:67], 0, v[4:5]
	v_readlane_b32 s48, v254, 60
	s_mov_b32 s49, 0xffff
	s_waitcnt lgkmcnt(0)
	v_add_f32_e32 v0, v147, v0
	v_fmamk_f32 v0, v0, 0x3b800000, v229
	v_rsq_f32_e32 v2, v0
	v_lshlrev_b32_e32 v0, 3, v215
	v_lshl_add_u64 v[4:5], v[4:5], 0, v[0:1]
	global_load_dwordx2 v[10:11], v[4:5], off
	global_load_dwordx2 v[12:13], v[4:5], off offset:16
	global_load_dwordx2 v[14:15], v[4:5], off offset:32
	global_load_dwordx2 v[16:17], v[4:5], off offset:48
	global_load_dwordx2 v[18:19], v[4:5], off offset:64
	global_load_dwordx2 v[20:21], v[4:5], off offset:80
	global_load_dwordx2 v[22:23], v[4:5], off offset:96
	global_load_dwordx2 v[24:25], v[4:5], off offset:112
	global_load_dwordx2 v[26:27], v[4:5], off offset:128
	global_load_dwordx2 v[28:29], v[4:5], off offset:144
	global_load_dwordx2 v[30:31], v[4:5], off offset:160
	global_load_dwordx2 v[32:33], v[4:5], off offset:176
	global_load_dwordx2 v[34:35], v[4:5], off offset:192
	global_load_dwordx2 v[36:37], v[4:5], off offset:208
	global_load_dwordx2 v[38:39], v[4:5], off offset:224
	global_load_dwordx2 v[40:41], v[4:5], off offset:240
	global_load_dwordx2 v[42:43], v[4:5], off offset:256
	global_load_dwordx2 v[44:45], v[4:5], off offset:272
	global_load_dwordx2 v[46:47], v[4:5], off offset:288
	global_load_dwordx2 v[48:49], v[4:5], off offset:304
	global_load_dwordx2 v[50:51], v[4:5], off offset:320
	global_load_dwordx2 v[52:53], v[4:5], off offset:336
	global_load_dwordx2 v[54:55], v[4:5], off offset:352
	global_load_dwordx2 v[56:57], v[4:5], off offset:368
	global_load_dwordx2 v[58:59], v[4:5], off offset:384
	global_load_dwordx2 v[60:61], v[4:5], off offset:400
	global_load_dwordx2 v[62:63], v[4:5], off offset:416
	global_load_dwordx2 v[64:65], v[4:5], off offset:432
	global_load_dwordx2 v[66:67], v[4:5], off offset:448
	global_load_dwordx2 v[68:69], v[4:5], off offset:464
	global_load_dwordx2 v[70:71], v[4:5], off offset:480
	global_load_dwordx2 v[72:73], v[4:5], off offset:496
	s_mov_b32 s47, s51
	s_mov_b32 s44, s57
	s_mov_b32 s8, s59
	s_waitcnt vmcnt(31)
	v_lshlrev_b32_e32 v8, 16, v10
	v_and_b32_e32 v9, 0xffff0000, v10
	v_pk_mul_f32 v[8:9], v[2:3], v[8:9] op_sel_hi:[0,1]
	v_cvt_pk_bf16_f32 v10, v8, v9
	v_lshlrev_b32_e32 v8, 16, v11
	v_and_b32_e32 v9, 0xffff0000, v11
	v_pk_mul_f32 v[8:9], v[2:3], v[8:9] op_sel_hi:[0,1]
	v_cvt_pk_bf16_f32 v11, v8, v9
	global_store_dwordx2 v[4:5], v[10:11], off
	s_waitcnt vmcnt(31)
	v_lshlrev_b32_e32 v8, 16, v12
	v_and_b32_e32 v9, 0xffff0000, v12
	v_pk_mul_f32 v[8:9], v[2:3], v[8:9] op_sel_hi:[0,1]
	v_cvt_pk_bf16_f32 v12, v8, v9
	v_lshlrev_b32_e32 v8, 16, v13
	v_and_b32_e32 v9, 0xffff0000, v13
	v_pk_mul_f32 v[8:9], v[2:3], v[8:9] op_sel_hi:[0,1]
	v_cvt_pk_bf16_f32 v13, v8, v9
	global_store_dwordx2 v[4:5], v[12:13], off offset:16
	s_waitcnt vmcnt(31)
	v_lshlrev_b32_e32 v8, 16, v14
	v_and_b32_e32 v9, 0xffff0000, v14
	v_pk_mul_f32 v[8:9], v[2:3], v[8:9] op_sel_hi:[0,1]
	v_cvt_pk_bf16_f32 v14, v8, v9
	v_lshlrev_b32_e32 v8, 16, v15
	v_and_b32_e32 v9, 0xffff0000, v15
	v_pk_mul_f32 v[8:9], v[2:3], v[8:9] op_sel_hi:[0,1]
	v_cvt_pk_bf16_f32 v15, v8, v9
	global_store_dwordx2 v[4:5], v[14:15], off offset:32
	s_waitcnt vmcnt(31)
	v_lshlrev_b32_e32 v8, 16, v16
	v_and_b32_e32 v9, 0xffff0000, v16
	v_pk_mul_f32 v[8:9], v[2:3], v[8:9] op_sel_hi:[0,1]
	v_cvt_pk_bf16_f32 v16, v8, v9
	v_lshlrev_b32_e32 v8, 16, v17
	v_and_b32_e32 v9, 0xffff0000, v17
	v_pk_mul_f32 v[8:9], v[2:3], v[8:9] op_sel_hi:[0,1]
	v_cvt_pk_bf16_f32 v17, v8, v9
	global_store_dwordx2 v[4:5], v[16:17], off offset:48
	s_waitcnt vmcnt(31)
	v_lshlrev_b32_e32 v8, 16, v18
	v_and_b32_e32 v9, 0xffff0000, v18
	v_pk_mul_f32 v[8:9], v[2:3], v[8:9] op_sel_hi:[0,1]
	v_cvt_pk_bf16_f32 v18, v8, v9
	v_lshlrev_b32_e32 v8, 16, v19
	v_and_b32_e32 v9, 0xffff0000, v19
	v_pk_mul_f32 v[8:9], v[2:3], v[8:9] op_sel_hi:[0,1]
	v_cvt_pk_bf16_f32 v19, v8, v9
	global_store_dwordx2 v[4:5], v[18:19], off offset:64
	s_waitcnt vmcnt(31)
	v_lshlrev_b32_e32 v8, 16, v20
	v_and_b32_e32 v9, 0xffff0000, v20
	v_pk_mul_f32 v[8:9], v[2:3], v[8:9] op_sel_hi:[0,1]
	v_cvt_pk_bf16_f32 v20, v8, v9
	v_lshlrev_b32_e32 v8, 16, v21
	v_and_b32_e32 v9, 0xffff0000, v21
	v_pk_mul_f32 v[8:9], v[2:3], v[8:9] op_sel_hi:[0,1]
	v_cvt_pk_bf16_f32 v21, v8, v9
	global_store_dwordx2 v[4:5], v[20:21], off offset:80
	s_waitcnt vmcnt(31)
	v_lshlrev_b32_e32 v8, 16, v22
	v_and_b32_e32 v9, 0xffff0000, v22
	v_pk_mul_f32 v[8:9], v[2:3], v[8:9] op_sel_hi:[0,1]
	v_cvt_pk_bf16_f32 v22, v8, v9
	v_lshlrev_b32_e32 v8, 16, v23
	v_and_b32_e32 v9, 0xffff0000, v23
	v_pk_mul_f32 v[8:9], v[2:3], v[8:9] op_sel_hi:[0,1]
	v_cvt_pk_bf16_f32 v23, v8, v9
	global_store_dwordx2 v[4:5], v[22:23], off offset:96
	s_waitcnt vmcnt(31)
	v_lshlrev_b32_e32 v8, 16, v24
	v_and_b32_e32 v9, 0xffff0000, v24
	v_pk_mul_f32 v[8:9], v[2:3], v[8:9] op_sel_hi:[0,1]
	v_cvt_pk_bf16_f32 v24, v8, v9
	v_lshlrev_b32_e32 v8, 16, v25
	v_and_b32_e32 v9, 0xffff0000, v25
	v_pk_mul_f32 v[8:9], v[2:3], v[8:9] op_sel_hi:[0,1]
	v_cvt_pk_bf16_f32 v25, v8, v9
	global_store_dwordx2 v[4:5], v[24:25], off offset:112
	s_waitcnt vmcnt(31)
	v_lshlrev_b32_e32 v8, 16, v26
	v_and_b32_e32 v9, 0xffff0000, v26
	v_pk_mul_f32 v[8:9], v[2:3], v[8:9] op_sel_hi:[0,1]
	v_cvt_pk_bf16_f32 v26, v8, v9
	v_lshlrev_b32_e32 v8, 16, v27
	v_and_b32_e32 v9, 0xffff0000, v27
	v_pk_mul_f32 v[8:9], v[2:3], v[8:9] op_sel_hi:[0,1]
	v_cvt_pk_bf16_f32 v27, v8, v9
	global_store_dwordx2 v[4:5], v[26:27], off offset:128
	s_waitcnt vmcnt(31)
; DI float bf_lo(unsigned u) { return __uint_as_float(u << 16); }
; DI float bf_hi(unsigned u) { return __uint_as_float(u & 0xffff0000u); }
; DI void phase_attn(const Params& p, int layer, char* smem) {
;     ...
;       for (int j = 0; j < 32; ++j) {
;         uint2* a = (uint2*)(ocat + (size_t)qtok * 1024 + 8 * j + 4 * h);
;         uint2 u = *a;
;         u.x = pk_bf16(bf_lo(u.x) * rstd, bf_hi(u.x) * rstd);
;         u.y = pk_bf16(bf_lo(u.y) * rstd, bf_hi(u.y) * rstd);
;         *a = u;
;       }
	v_lshlrev_b32_e32 v8, 16, v28
	v_and_b32_e32 v9, 0xffff0000, v28
	v_pk_mul_f32 v[8:9], v[2:3], v[8:9] op_sel_hi:[0,1]
	v_cvt_pk_bf16_f32 v28, v8, v9
	v_lshlrev_b32_e32 v8, 16, v29
	v_and_b32_e32 v9, 0xffff0000, v29
	v_pk_mul_f32 v[8:9], v[2:3], v[8:9] op_sel_hi:[0,1]
	v_cvt_pk_bf16_f32 v29, v8, v9
	global_store_dwordx2 v[4:5], v[28:29], off offset:144
	s_waitcnt vmcnt(31)
	v_lshlrev_b32_e32 v8, 16, v30
	v_and_b32_e32 v9, 0xffff0000, v30
	v_pk_mul_f32 v[8:9], v[2:3], v[8:9] op_sel_hi:[0,1]
	v_cvt_pk_bf16_f32 v30, v8, v9
	v_lshlrev_b32_e32 v8, 16, v31
	v_and_b32_e32 v9, 0xffff0000, v31
	v_pk_mul_f32 v[8:9], v[2:3], v[8:9] op_sel_hi:[0,1]
	v_cvt_pk_bf16_f32 v31, v8, v9
	global_store_dwordx2 v[4:5], v[30:31], off offset:160
	s_waitcnt vmcnt(31)
	v_lshlrev_b32_e32 v8, 16, v32
	v_and_b32_e32 v9, 0xffff0000, v32
	v_pk_mul_f32 v[8:9], v[2:3], v[8:9] op_sel_hi:[0,1]
	v_cvt_pk_bf16_f32 v32, v8, v9
	v_lshlrev_b32_e32 v8, 16, v33
	v_and_b32_e32 v9, 0xffff0000, v33
	v_pk_mul_f32 v[8:9], v[2:3], v[8:9] op_sel_hi:[0,1]
	v_cvt_pk_bf16_f32 v33, v8, v9
	global_store_dwordx2 v[4:5], v[32:33], off offset:176
	s_waitcnt vmcnt(31)
	v_lshlrev_b32_e32 v8, 16, v34
	v_and_b32_e32 v9, 0xffff0000, v34
	v_pk_mul_f32 v[8:9], v[2:3], v[8:9] op_sel_hi:[0,1]
	v_cvt_pk_bf16_f32 v34, v8, v9
	v_lshlrev_b32_e32 v8, 16, v35
	v_and_b32_e32 v9, 0xffff0000, v35
	v_pk_mul_f32 v[8:9], v[2:3], v[8:9] op_sel_hi:[0,1]
	v_cvt_pk_bf16_f32 v35, v8, v9
	global_store_dwordx2 v[4:5], v[34:35], off offset:192
	s_waitcnt vmcnt(31)
	v_lshlrev_b32_e32 v8, 16, v36
	v_and_b32_e32 v9, 0xffff0000, v36
	v_pk_mul_f32 v[8:9], v[2:3], v[8:9] op_sel_hi:[0,1]
	v_cvt_pk_bf16_f32 v36, v8, v9
	v_lshlrev_b32_e32 v8, 16, v37
	v_and_b32_e32 v9, 0xffff0000, v37
	v_pk_mul_f32 v[8:9], v[2:3], v[8:9] op_sel_hi:[0,1]
	v_cvt_pk_bf16_f32 v37, v8, v9
	global_store_dwordx2 v[4:5], v[36:37], off offset:208
	s_waitcnt vmcnt(31)
	v_lshlrev_b32_e32 v8, 16, v38
	v_and_b32_e32 v9, 0xffff0000, v38
	v_pk_mul_f32 v[8:9], v[2:3], v[8:9] op_sel_hi:[0,1]
	v_cvt_pk_bf16_f32 v38, v8, v9
	v_lshlrev_b32_e32 v8, 16, v39
	v_and_b32_e32 v9, 0xffff0000, v39
	v_pk_mul_f32 v[8:9], v[2:3], v[8:9] op_sel_hi:[0,1]
	v_cvt_pk_bf16_f32 v39, v8, v9
	global_store_dwordx2 v[4:5], v[38:39], off offset:224
	s_waitcnt vmcnt(31)
	v_lshlrev_b32_e32 v8, 16, v40
	v_and_b32_e32 v9, 0xffff0000, v40
	v_pk_mul_f32 v[8:9], v[2:3], v[8:9] op_sel_hi:[0,1]
	v_cvt_pk_bf16_f32 v40, v8, v9
	v_lshlrev_b32_e32 v8, 16, v41
	v_and_b32_e32 v9, 0xffff0000, v41
	v_pk_mul_f32 v[8:9], v[2:3], v[8:9] op_sel_hi:[0,1]
	v_cvt_pk_bf16_f32 v41, v8, v9
	global_store_dwordx2 v[4:5], v[40:41], off offset:240
	s_waitcnt vmcnt(31)
	v_lshlrev_b32_e32 v8, 16, v42
	v_and_b32_e32 v9, 0xffff0000, v42
	v_pk_mul_f32 v[8:9], v[2:3], v[8:9] op_sel_hi:[0,1]
	v_cvt_pk_bf16_f32 v42, v8, v9
	v_lshlrev_b32_e32 v8, 16, v43
	v_and_b32_e32 v9, 0xffff0000, v43
	v_pk_mul_f32 v[8:9], v[2:3], v[8:9] op_sel_hi:[0,1]
	v_cvt_pk_bf16_f32 v43, v8, v9
	global_store_dwordx2 v[4:5], v[42:43], off offset:256
	s_waitcnt vmcnt(31)
	v_lshlrev_b32_e32 v8, 16, v44
	v_and_b32_e32 v9, 0xffff0000, v44
	v_pk_mul_f32 v[8:9], v[2:3], v[8:9] op_sel_hi:[0,1]
	v_cvt_pk_bf16_f32 v44, v8, v9
	v_lshlrev_b32_e32 v8, 16, v45
	v_and_b32_e32 v9, 0xffff0000, v45
	v_pk_mul_f32 v[8:9], v[2:3], v[8:9] op_sel_hi:[0,1]
	v_cvt_pk_bf16_f32 v45, v8, v9
	global_store_dwordx2 v[4:5], v[44:45], off offset:272
	s_waitcnt vmcnt(31)
	v_lshlrev_b32_e32 v8, 16, v46
	v_and_b32_e32 v9, 0xffff0000, v46
	v_pk_mul_f32 v[8:9], v[2:3], v[8:9] op_sel_hi:[0,1]
	v_cvt_pk_bf16_f32 v46, v8, v9
	v_lshlrev_b32_e32 v8, 16, v47
	v_and_b32_e32 v9, 0xffff0000, v47
	v_pk_mul_f32 v[8:9], v[2:3], v[8:9] op_sel_hi:[0,1]
	v_cvt_pk_bf16_f32 v47, v8, v9
	global_store_dwordx2 v[4:5], v[46:47], off offset:288
	s_waitcnt vmcnt(31)
	v_lshlrev_b32_e32 v8, 16, v48
	v_and_b32_e32 v9, 0xffff0000, v48
	v_pk_mul_f32 v[8:9], v[2:3], v[8:9] op_sel_hi:[0,1]
	v_cvt_pk_bf16_f32 v48, v8, v9
	v_lshlrev_b32_e32 v8, 16, v49
	v_and_b32_e32 v9, 0xffff0000, v49
	v_pk_mul_f32 v[8:9], v[2:3], v[8:9] op_sel_hi:[0,1]
	v_cvt_pk_bf16_f32 v49, v8, v9
	global_store_dwordx2 v[4:5], v[48:49], off offset:304
	s_waitcnt vmcnt(31)
; DI float bf_lo(unsigned u) { return __uint_as_float(u << 16); }
; DI float bf_hi(unsigned u) { return __uint_as_float(u & 0xffff0000u); }
; DI void phase_attn(const Params& p, int layer, char* smem) {
;     ...
;       for (int j = 0; j < 32; ++j) {
;         uint2* a = (uint2*)(ocat + (size_t)qtok * 1024 + 8 * j + 4 * h);
;         uint2 u = *a;
;         u.x = pk_bf16(bf_lo(u.x) * rstd, bf_hi(u.x) * rstd);
;         u.y = pk_bf16(bf_lo(u.y) * rstd, bf_hi(u.y) * rstd);
;         *a = u;
;       }
	v_lshlrev_b32_e32 v8, 16, v50
	v_and_b32_e32 v9, 0xffff0000, v50
	v_pk_mul_f32 v[8:9], v[2:3], v[8:9] op_sel_hi:[0,1]
	v_cvt_pk_bf16_f32 v50, v8, v9
	v_lshlrev_b32_e32 v8, 16, v51
	v_and_b32_e32 v9, 0xffff0000, v51
	v_pk_mul_f32 v[8:9], v[2:3], v[8:9] op_sel_hi:[0,1]
	v_cvt_pk_bf16_f32 v51, v8, v9
	global_store_dwordx2 v[4:5], v[50:51], off offset:320
	s_waitcnt vmcnt(31)
	v_lshlrev_b32_e32 v8, 16, v52
	v_and_b32_e32 v9, 0xffff0000, v52
	v_pk_mul_f32 v[8:9], v[2:3], v[8:9] op_sel_hi:[0,1]
	v_cvt_pk_bf16_f32 v52, v8, v9
	v_lshlrev_b32_e32 v8, 16, v53
	v_and_b32_e32 v9, 0xffff0000, v53
	v_pk_mul_f32 v[8:9], v[2:3], v[8:9] op_sel_hi:[0,1]
	v_cvt_pk_bf16_f32 v53, v8, v9
	global_store_dwordx2 v[4:5], v[52:53], off offset:336
	s_waitcnt vmcnt(31)
	v_lshlrev_b32_e32 v8, 16, v54
	v_and_b32_e32 v9, 0xffff0000, v54
	v_pk_mul_f32 v[8:9], v[2:3], v[8:9] op_sel_hi:[0,1]
	v_cvt_pk_bf16_f32 v54, v8, v9
	v_lshlrev_b32_e32 v8, 16, v55
	v_and_b32_e32 v9, 0xffff0000, v55
	v_pk_mul_f32 v[8:9], v[2:3], v[8:9] op_sel_hi:[0,1]
	v_cvt_pk_bf16_f32 v55, v8, v9
	global_store_dwordx2 v[4:5], v[54:55], off offset:352
	s_waitcnt vmcnt(31)
	v_lshlrev_b32_e32 v8, 16, v56
	v_and_b32_e32 v9, 0xffff0000, v56
	v_pk_mul_f32 v[8:9], v[2:3], v[8:9] op_sel_hi:[0,1]
	v_cvt_pk_bf16_f32 v56, v8, v9
	v_lshlrev_b32_e32 v8, 16, v57
	v_and_b32_e32 v9, 0xffff0000, v57
	v_pk_mul_f32 v[8:9], v[2:3], v[8:9] op_sel_hi:[0,1]
	v_cvt_pk_bf16_f32 v57, v8, v9
	global_store_dwordx2 v[4:5], v[56:57], off offset:368
	s_waitcnt vmcnt(31)
	v_lshlrev_b32_e32 v8, 16, v58
	v_and_b32_e32 v9, 0xffff0000, v58
	v_pk_mul_f32 v[8:9], v[2:3], v[8:9] op_sel_hi:[0,1]
	v_cvt_pk_bf16_f32 v58, v8, v9
	v_lshlrev_b32_e32 v8, 16, v59
	v_and_b32_e32 v9, 0xffff0000, v59
	v_pk_mul_f32 v[8:9], v[2:3], v[8:9] op_sel_hi:[0,1]
	v_cvt_pk_bf16_f32 v59, v8, v9
	global_store_dwordx2 v[4:5], v[58:59], off offset:384
	s_waitcnt vmcnt(31)
	v_lshlrev_b32_e32 v8, 16, v60
	v_and_b32_e32 v9, 0xffff0000, v60
	v_pk_mul_f32 v[8:9], v[2:3], v[8:9] op_sel_hi:[0,1]
	v_cvt_pk_bf16_f32 v60, v8, v9
	v_lshlrev_b32_e32 v8, 16, v61
	v_and_b32_e32 v9, 0xffff0000, v61
	v_pk_mul_f32 v[8:9], v[2:3], v[8:9] op_sel_hi:[0,1]
	v_cvt_pk_bf16_f32 v61, v8, v9
	global_store_dwordx2 v[4:5], v[60:61], off offset:400
	s_waitcnt vmcnt(31)
	v_lshlrev_b32_e32 v8, 16, v62
	v_and_b32_e32 v9, 0xffff0000, v62
	v_pk_mul_f32 v[8:9], v[2:3], v[8:9] op_sel_hi:[0,1]
	v_cvt_pk_bf16_f32 v62, v8, v9
	v_lshlrev_b32_e32 v8, 16, v63
	v_and_b32_e32 v9, 0xffff0000, v63
	v_pk_mul_f32 v[8:9], v[2:3], v[8:9] op_sel_hi:[0,1]
	v_cvt_pk_bf16_f32 v63, v8, v9
	global_store_dwordx2 v[4:5], v[62:63], off offset:416
	s_waitcnt vmcnt(31)
	v_lshlrev_b32_e32 v8, 16, v64
	v_and_b32_e32 v9, 0xffff0000, v64
	v_pk_mul_f32 v[8:9], v[2:3], v[8:9] op_sel_hi:[0,1]
	v_cvt_pk_bf16_f32 v64, v8, v9
	v_lshlrev_b32_e32 v8, 16, v65
	v_and_b32_e32 v9, 0xffff0000, v65
	v_pk_mul_f32 v[8:9], v[2:3], v[8:9] op_sel_hi:[0,1]
	v_cvt_pk_bf16_f32 v65, v8, v9
	global_store_dwordx2 v[4:5], v[64:65], off offset:432
	s_waitcnt vmcnt(31)
	v_lshlrev_b32_e32 v8, 16, v66
	v_and_b32_e32 v9, 0xffff0000, v66
	v_pk_mul_f32 v[8:9], v[2:3], v[8:9] op_sel_hi:[0,1]
	v_cvt_pk_bf16_f32 v66, v8, v9
	v_lshlrev_b32_e32 v8, 16, v67
	v_and_b32_e32 v9, 0xffff0000, v67
	v_pk_mul_f32 v[8:9], v[2:3], v[8:9] op_sel_hi:[0,1]
	v_cvt_pk_bf16_f32 v67, v8, v9
	global_store_dwordx2 v[4:5], v[66:67], off offset:448
	s_waitcnt vmcnt(31)
	v_lshlrev_b32_e32 v8, 16, v68
	v_and_b32_e32 v9, 0xffff0000, v68
	v_pk_mul_f32 v[8:9], v[2:3], v[8:9] op_sel_hi:[0,1]
	v_cvt_pk_bf16_f32 v68, v8, v9
	v_lshlrev_b32_e32 v8, 16, v69
	v_and_b32_e32 v9, 0xffff0000, v69
	v_pk_mul_f32 v[8:9], v[2:3], v[8:9] op_sel_hi:[0,1]
	v_cvt_pk_bf16_f32 v69, v8, v9
	global_store_dwordx2 v[4:5], v[68:69], off offset:464
	s_waitcnt vmcnt(31)
	v_lshlrev_b32_e32 v8, 16, v70
	v_and_b32_e32 v9, 0xffff0000, v70
	v_pk_mul_f32 v[8:9], v[2:3], v[8:9] op_sel_hi:[0,1]
	v_cvt_pk_bf16_f32 v70, v8, v9
	v_lshlrev_b32_e32 v8, 16, v71
	v_and_b32_e32 v9, 0xffff0000, v71
	v_pk_mul_f32 v[8:9], v[2:3], v[8:9] op_sel_hi:[0,1]
	v_cvt_pk_bf16_f32 v71, v8, v9
	global_store_dwordx2 v[4:5], v[70:71], off offset:480
	s_waitcnt vmcnt(31)
	v_lshlrev_b32_e32 v8, 16, v72
	v_and_b32_e32 v9, 0xffff0000, v72
	v_pk_mul_f32 v[8:9], v[2:3], v[8:9] op_sel_hi:[0,1]
	v_cvt_pk_bf16_f32 v72, v8, v9
	v_lshlrev_b32_e32 v8, 16, v73
	v_and_b32_e32 v9, 0xffff0000, v73
	v_pk_mul_f32 v[2:3], v[2:3], v[8:9] op_sel_hi:[0,1]
	v_cvt_pk_bf16_f32 v73, v2, v3
	global_store_dwordx2 v[4:5], v[72:73], off offset:496

; DI float bf_lo(unsigned u) { return __uint_as_float(u << 16); }
; DI float bf_hi(unsigned u) { return __uint_as_float(u & 0xffff0000u); }
; DI void phase_attn(const Params& p, int layer, char* smem) {
;     ...
; #pragma unroll 4
;       for (int j = 0; j < 64; ++j) {
;         const int tk = (j < 32) ? tA3 : tA3 + 32;
;         const float rs = (j < 32) ? rstdA : rstdB;
;         uint2* a = (uint2*)(ocat + (size_t)tk * 1024 + 256 + 8 * (j & 31) + 4 * h3);
;         uint2 u = *a;
;         u.x = pk_bf16(bf_lo(u.x) * rs, bf_hi(u.x) * rs);
;         u.y = pk_bf16(bf_lo(u.y) * rs, bf_hi(u.y) * rs);
;         *a = u;
;       }
.LBB0_382:
	v_and_or_b32 v6, s1, 32, v4
	s_cmp_lt_u32 s1, 32
	v_ashrrev_i32_e32 v7, 31, v6
	s_cselect_b64 vcc, -1, 0
	v_lshlrev_b64 v[6:7], 11, v[6:7]
	s_and_b32 s2, s0, 0xe0
	v_lshl_add_u64 v[6:7], s[66:67], 0, v[6:7]
	s_lshl_b32 s34, s2, 1
	v_lshl_add_u64 v[6:7], v[6:7], 0, s[34:35]
	v_lshl_add_u64 v[6:7], v[6:7], 0, v[0:1]
	global_load_dwordx2 v[10:11], v[6:7], off offset:512
	global_load_dwordx2 v[14:15], v[6:7], off offset:528
	global_load_dwordx2 v[16:17], v[6:7], off offset:544
	global_load_dwordx2 v[18:19], v[6:7], off offset:560
	v_cndmask_b32_e32 v8, v3, v2, vcc
	s_add_i32 s1, s1, 4
	s_add_i32 s0, s0, 32
	s_cmp_eq_u32 s1, 64
	s_waitcnt vmcnt(3)
	v_lshlrev_b32_e32 v12, 16, v10
	v_and_b32_e32 v13, 0xffff0000, v10
	v_pk_mul_f32 v[12:13], v[8:9], v[12:13] op_sel_hi:[0,1]
	v_cvt_pk_bf16_f32 v10, v12, v13
	v_lshlrev_b32_e32 v12, 16, v11
	v_and_b32_e32 v13, 0xffff0000, v11
	v_pk_mul_f32 v[12:13], v[8:9], v[12:13] op_sel_hi:[0,1]
	v_cvt_pk_bf16_f32 v11, v12, v13
	global_store_dwordx2 v[6:7], v[10:11], off offset:512
	s_waitcnt vmcnt(3)
	v_lshlrev_b32_e32 v12, 16, v14
	v_and_b32_e32 v13, 0xffff0000, v14
	v_pk_mul_f32 v[12:13], v[8:9], v[12:13] op_sel_hi:[0,1]
	v_cvt_pk_bf16_f32 v14, v12, v13
	v_lshlrev_b32_e32 v12, 16, v15
	v_and_b32_e32 v13, 0xffff0000, v15
	v_pk_mul_f32 v[12:13], v[8:9], v[12:13] op_sel_hi:[0,1]
	v_cvt_pk_bf16_f32 v15, v12, v13
	global_store_dwordx2 v[6:7], v[14:15], off offset:528
	s_waitcnt vmcnt(3)
	v_lshlrev_b32_e32 v12, 16, v16
	v_and_b32_e32 v13, 0xffff0000, v16
	v_pk_mul_f32 v[12:13], v[8:9], v[12:13] op_sel_hi:[0,1]
	v_cvt_pk_bf16_f32 v16, v12, v13
	v_lshlrev_b32_e32 v12, 16, v17
	v_and_b32_e32 v13, 0xffff0000, v17
	v_pk_mul_f32 v[12:13], v[8:9], v[12:13] op_sel_hi:[0,1]
	v_cvt_pk_bf16_f32 v17, v12, v13
	global_store_dwordx2 v[6:7], v[16:17], off offset:544
	s_waitcnt vmcnt(3)
	v_lshlrev_b32_e32 v12, 16, v18
	v_and_b32_e32 v13, 0xffff0000, v18
	v_pk_mul_f32 v[12:13], v[8:9], v[12:13] op_sel_hi:[0,1]
	v_cvt_pk_bf16_f32 v18, v12, v13
	v_lshlrev_b32_e32 v12, 16, v19
	v_and_b32_e32 v13, 0xffff0000, v19
	v_pk_mul_f32 v[8:9], v[8:9], v[12:13] op_sel_hi:[0,1]
	v_cvt_pk_bf16_f32 v19, v8, v9
	global_store_dwordx2 v[6:7], v[18:19], off offset:560
	s_cbranch_scc0 .LBB0_382

; DI float bf_lo(unsigned u) { return __uint_as_float(u << 16); }
; DI float bf_hi(unsigned u) { return __uint_as_float(u & 0xffff0000u); }
; DI int otid() { int t = threadIdx.x; asm volatile("" : "+v"(t)); return t; }
; DI void phase_resid(const float* x_f32, bf16_t* xb, const bf16_t* y, const float* g_post, float* out_f32, float* rstd_out, bool write_xb) {
;   const int lane = otid() & 63;
;   const int gw = blockIdx.x * (NT / 64) + (otid() >> 6), nw = gridDim.x * (NT / 64);
;   for (int row = gw; row < T_TOK; row += nw) {
;     float xv[2][8];
; #pragma unroll
;     for (int j = 0; j < 2; ++j) {
;       const size_t off = (size_t)row * 1024 + j * 512 + lane * 8;
;       if (x_f32) {
;         const float4 a = *(const float4*)(x_f32 + off), c = *(const float4*)(x_f32 + off + 4);
;         xv[j][0] = a.x; xv[j][1] = a.y; xv[j][2] = a.z; xv[j][3] = a.w; xv[j][4] = c.x; xv[j][5] = c.y; xv[j][6] = c.z; xv[j][7] = c.w;
;       } else {
;         const uint4 u = *(const uint4*)(xb + off);
;         xv[j][0] = bf_lo(u.x); xv[j][1] = bf_hi(u.x); xv[j][2] = bf_lo(u.y); xv[j][3] = bf_hi(u.y);
;         xv[j][4] = bf_lo(u.z); xv[j][5] = bf_hi(u.z); xv[j][6] = bf_lo(u.w); xv[j][7] = bf_hi(u.w);
;       }
;     }
.LBB0_755:
	v_mov_b32_e32 v0, v228
	v_mov_b32_e32 v2, v228
	v_readlane_b32 s0, v251, 4
	v_ashrrev_i32_e32 v2, 6, v2
	s_nop 0
	v_add_u32_e32 v18, s0, v2
	s_mov_b32 s0, 0x10000
	v_cmp_gt_i32_e32 vcc, s0, v18
	s_and_saveexec_b64 s[2:3], vcc
	s_cbranch_execz .LBB0_768
	v_cmp_lt_i32_e32 vcc, v234, v233
	v_and_b32_e32 v4, 63, v0
	s_load_dword s4, s[44:45], 0x10
	v_cndmask_b32_e32 v0, v232, v234, vcc
	v_cmp_lt_i32_e32 vcc, v235, v233
	v_ashrrev_i32_e32 v19, 31, v18
	v_lshlrev_b64 v[22:23], 11, v[18:19]
	v_cndmask_b32_e32 v2, v232, v235, vcc
	v_lshlrev_b32_e32 v28, 2, v2
	v_xor_b32_e32 v2, 8, v232
	v_cmp_lt_i32_e32 vcc, v2, v233
	s_waitcnt lgkmcnt(0)
	s_lshr_b32 s4, s4, 16
	s_cmp_lg_u32 s4, 0
	v_cndmask_b32_e32 v2, v232, v2, vcc
	v_lshlrev_b32_e32 v29, 2, v2
	v_xor_b32_e32 v2, 4, v232
	v_cmp_lt_i32_e32 vcc, v2, v233
	s_cselect_b64 s[4:5], -1, 0
	s_cmp_lg_u64 s[4:5], 0
	v_cndmask_b32_e32 v2, v232, v2, vcc
	v_lshlrev_b32_e32 v30, 2, v2
	v_xor_b32_e32 v2, 2, v232
	v_cmp_lt_i32_e32 vcc, v2, v233
	s_addc_u32 s4, s96, 0
	s_lshl_b32 s6, s4, 3
	v_cndmask_b32_e32 v2, v232, v2, vcc
	v_cmp_lt_i32_e32 vcc, v250, v233
	v_lshlrev_b32_e32 v31, 2, v2
	v_readlane_b32 s4, v254, 11
	v_cndmask_b32_e32 v2, v232, v250, vcc
	v_lshlrev_b32_e32 v32, 2, v2
	v_mov_b64_e32 v[2:3], 0x1b10e000
	v_lshl_add_u64 v[20:21], v[18:19], 2, v[2:3]
	v_lshlrev_b64 v[2:3], 12, v[18:19]
	s_ashr_i32 s7, s6, 31
	v_lshl_or_b32 v2, v4, 5, v2
	v_readlane_b32 s5, v254, 12
	v_cmp_eq_u32_e64 s[0:1], 0, v4
	v_lshlrev_b32_e32 v0, 2, v0
	s_lshl_b64 s[8:9], s[6:7], 2
	v_lshl_or_b32 v22, v4, 4, v22
	s_lshl_b64 s[10:11], s[6:7], 11
	v_lshl_add_u64 v[24:25], s[4:5], 0, v[2:3]
	s_lshl_b64 s[28:29], s[6:7], 12
	s_mov_b64 s[30:31], 0
	v_readfirstlane_b32 s0, v18
	v_readlane_b32 s4, v254, 11
	v_readlane_b32 s5, v254, 12
	s_add_u32 s6, s86, 0x2f0e000
	s_addc_u32 s7, s87, 0
	v_and_b32_e32 v93, 63, v228
	v_lshlrev_b32_e32 v95, 5, v93
	v_lshlrev_b32_e32 v93, 4, v93
	v_readlane_b32 s98, v253, 43
	s_mov_b64 exec, -1
	s_lshl_b32 s1, s0, 12
	v_add_u32_e32 v91, s1, v95
	global_load_dwordx4 v[16:19], v91, s[4:5] offset:-2048
	global_load_dwordx4 v[20:23], v91, s[4:5] offset:-2032
	global_load_dwordx4 v[24:27], v91, s[4:5]
	global_load_dwordx4 v[28:31], v91, s[4:5] offset:16
	s_add_u32 s1, s0, s98
	s_min_u32 s1, s1, 0xffff
	s_lshl_b32 s1, s1, 12
	v_add_u32_e32 v91, s1, v95
	global_load_dwordx4 v[32:35], v91, s[4:5] offset:-2048
	global_load_dwordx4 v[36:39], v91, s[4:5] offset:-2032
	global_load_dwordx4 v[40:43], v91, s[4:5]
	global_load_dwordx4 v[44:47], v91, s[4:5] offset:16
	s_mov_b32 s99, 1

; DI void phase_resid(const float* x_f32, bf16_t* xb, const bf16_t* y, const float* g_post, float* out_f32, float* rstd_out, bool write_xb) {
;     ...
;   for (int row = gw; row < T_TOK; row += nw) {
;     float xv[2][8];
; #pragma unroll
;     for (int j = 0; j < 2; ++j) {
;       const size_t off = (size_t)row * 1024 + j * 512 + lane * 8;
;       if (x_f32) {
;         const float4 a = *(const float4*)(x_f32 + off), c = *(const float4*)(x_f32 + off + 4);
;         xv[j][0] = a.x; xv[j][1] = a.y; xv[j][2] = a.z; xv[j][3] = a.w; xv[j][4] = c.x; xv[j][5] = c.y; xv[j][6] = c.z; xv[j][7] = c.w;
;       } else {
;         const uint4 u = *(const uint4*)(xb + off);
;         xv[j][0] = bf_lo(u.x); xv[j][1] = bf_hi(u.x); xv[j][2] = bf_lo(u.y); xv[j][3] = bf_hi(u.y);
;         xv[j][4] = bf_lo(u.z); xv[j][5] = bf_hi(u.z); xv[j][6] = bf_lo(u.w); xv[j][7] = bf_hi(u.w);
;       }
;     }
;     if (y) {
;       float yv[2][8];
;       float ss = 0.f;
; #pragma unroll
;       for (int j = 0; j < 2; ++j) {
;         const uint4 u = *(const uint4*)(y + (size_t)row * 1024 + j * 512 + lane * 8);
;         yv[j][0] = bf_lo(u.x); yv[j][1] = bf_hi(u.x); yv[j][2] = bf_lo(u.y); yv[j][3] = bf_hi(u.y);
;         yv[j][4] = bf_lo(u.z); yv[j][5] = bf_hi(u.z); yv[j][6] = bf_lo(u.w); yv[j][7] = bf_hi(u.w);
; #pragma unroll
;         for (int e = 0; e < 8; ++e) ss += yv[j][e] * yv[j][e];
;       }
;       ss = wave_sum(ss);
;       const float rs = frsq(ss * (1.f / 1024.f) + EPS);
; #pragma unroll
;       for (int j = 0; j < 2; ++j) {
;         const float4 g0 = *(const float4*)(g_post + j * 512 + lane * 8), g1 = *(const float4*)(g_post + j * 512 + lane * 8 + 4);
;         xv[j][0] += yv[j][0] * rs * g0.x; xv[j][1] += yv[j][1] * rs * g0.y; xv[j][2] += yv[j][2] * rs * g0.z; xv[j][3] += yv[j][3] * rs * g0.w;
;         xv[j][4] += yv[j][4] * rs * g1.x; xv[j][5] += yv[j][5] * rs * g1.y; xv[j][6] += yv[j][6] * rs * g1.z; xv[j][7] += yv[j][7] * rs * g1.w;
;       }
;     }
;     if (out_f32) {
; #pragma unroll
;       for (int j = 0; j < 2; ++j) {
;         const size_t off = (size_t)row * 1024 + j * 512 + lane * 8;
;         *(float4*)(out_f32 + off) = make_float4(xv[j][0], xv[j][1], xv[j][2], xv[j][3]);
;         *(float4*)(out_f32 + off + 4) = make_float4(xv[j][4], xv[j][5], xv[j][6], xv[j][7]);
;       }
;     }
;     if (write_xb) {
; #pragma unroll
;       for (int j = 0; j < 2; ++j) {
.Lresid_p0_0_wdone:
	v_mul_f32_e32 v80, v16, v16
	v_mul_f32_e32 v81, v17, v17
	v_fmac_f32_e32 v80, v18, v18
	v_fmac_f32_e32 v81, v19, v19
	v_fmac_f32_e32 v80, v20, v20
	v_fmac_f32_e32 v81, v21, v21
	v_fmac_f32_e32 v80, v22, v22
	v_fmac_f32_e32 v81, v23, v23
	v_fmac_f32_e32 v80, v24, v24
	v_fmac_f32_e32 v81, v25, v25
	v_fmac_f32_e32 v80, v26, v26
	v_fmac_f32_e32 v81, v27, v27
	v_fmac_f32_e32 v80, v28, v28
	v_fmac_f32_e32 v81, v29, v29
	v_fmac_f32_e32 v80, v30, v30
	v_fmac_f32_e32 v81, v31, v31
	v_cvt_pk_bf16_f32 v82, v16, v17
	v_cvt_pk_bf16_f32 v83, v18, v19
	v_cvt_pk_bf16_f32 v84, v20, v21
	v_cvt_pk_bf16_f32 v85, v22, v23
	v_cvt_pk_bf16_f32 v86, v24, v25
	v_cvt_pk_bf16_f32 v87, v26, v27
	v_cvt_pk_bf16_f32 v88, v28, v29
	v_cvt_pk_bf16_f32 v89, v30, v31
	v_add_f32_e32 v80, v80, v81
	s_lshl_b32 s1, s0, 11
	v_add_u32_e32 v90, s1, v93
	s_add_u32 s1, s0, s98
	s_add_u32 s1, s1, s98
	s_min_u32 s1, s1, 0xffff
	s_lshl_b32 s1, s1, 12
	v_add_u32_e32 v91, s1, v95
	global_load_dwordx4 v[16:19], v91, s[4:5] offset:-2048
	global_load_dwordx4 v[20:23], v91, s[4:5] offset:-2032
	global_load_dwordx4 v[24:27], v91, s[4:5]
	global_load_dwordx4 v[28:31], v91, s[4:5] offset:16
	global_store_dwordx4 v90, v[82:85], s[6:7]
	global_store_dwordx4 v90, v[86:89], s[6:7] offset:1024
	s_nop 1
	v_add_f32_dpp v80, v80, v80 quad_perm:[1,0,3,2] row_mask:0xf bank_mask:0xf
	s_nop 1
	v_add_f32_dpp v80, v80, v80 quad_perm:[2,3,0,1] row_mask:0xf bank_mask:0xf
	s_nop 1
	v_add_f32_dpp v80, v80, v80 row_half_mirror row_mask:0xf bank_mask:0xf
	s_nop 1
	v_add_f32_dpp v80, v80, v80 row_mirror row_mask:0xf bank_mask:0xf
	s_nop 1
	v_add_f32_dpp v80, v80, v80 row_bcast:15 row_mask:0xa bank_mask:0xf
	s_nop 1
	v_add_f32_dpp v80, v80, v80 row_bcast:31 row_mask:0xc bank_mask:0xf
	s_nop 1
	v_readlane_b32 s1, v80, 63
	s_nop 1
	v_mov_b32_e32 v80, s1
	v_fmamk_f32 v80, v80, 0x3a800000, v229
	v_rsq_f32_e32 v80, v80
	s_lshl_b32 s1, s0, 2
	s_add_u32 s1, s1, 0x1b10e000
	v_mov_b32_e32 v92, s1
	s_mov_b64 exec, 1
	global_store_dword v92, v80, s[86:87]
	s_mov_b64 exec, -1
	s_add_u32 s0, s0, s98
	s_cmp_gt_u32 s0, 0xffff
	s_cbranch_scc1 .Lresid_p0_done
	s_cmp_eq_u32 s99, 1
	s_cbranch_scc1 .Lresid_p0_1_wfirst
	s_waitcnt vmcnt(10)
	s_branch .Lresid_p0_1_wdone

; DI void phase_resid(const float* x_f32, bf16_t* xb, const bf16_t* y, const float* g_post, float* out_f32, float* rstd_out, bool write_xb) {
;     ...
;   for (int row = gw; row < T_TOK; row += nw) {
;     float xv[2][8];
; #pragma unroll
;     for (int j = 0; j < 2; ++j) {
;       const size_t off = (size_t)row * 1024 + j * 512 + lane * 8;
;       if (x_f32) {
;         const float4 a = *(const float4*)(x_f32 + off), c = *(const float4*)(x_f32 + off + 4);
;         xv[j][0] = a.x; xv[j][1] = a.y; xv[j][2] = a.z; xv[j][3] = a.w; xv[j][4] = c.x; xv[j][5] = c.y; xv[j][6] = c.z; xv[j][7] = c.w;
;       } else {
;         const uint4 u = *(const uint4*)(xb + off);
;         xv[j][0] = bf_lo(u.x); xv[j][1] = bf_hi(u.x); xv[j][2] = bf_lo(u.y); xv[j][3] = bf_hi(u.y);
;         xv[j][4] = bf_lo(u.z); xv[j][5] = bf_hi(u.z); xv[j][6] = bf_lo(u.w); xv[j][7] = bf_hi(u.w);
;       }
;     }
;     if (y) {
;       float yv[2][8];
;       float ss = 0.f;
; #pragma unroll
;       for (int j = 0; j < 2; ++j) {
;         const uint4 u = *(const uint4*)(y + (size_t)row * 1024 + j * 512 + lane * 8);
;         yv[j][0] = bf_lo(u.x); yv[j][1] = bf_hi(u.x); yv[j][2] = bf_lo(u.y); yv[j][3] = bf_hi(u.y);
;         yv[j][4] = bf_lo(u.z); yv[j][5] = bf_hi(u.z); yv[j][6] = bf_lo(u.w); yv[j][7] = bf_hi(u.w);
; #pragma unroll
;         for (int e = 0; e < 8; ++e) ss += yv[j][e] * yv[j][e];
;       }
;       ss = wave_sum(ss);
;       const float rs = frsq(ss * (1.f / 1024.f) + EPS);
; #pragma unroll
;       for (int j = 0; j < 2; ++j) {
;         const float4 g0 = *(const float4*)(g_post + j * 512 + lane * 8), g1 = *(const float4*)(g_post + j * 512 + lane * 8 + 4);
;         xv[j][0] += yv[j][0] * rs * g0.x; xv[j][1] += yv[j][1] * rs * g0.y; xv[j][2] += yv[j][2] * rs * g0.z; xv[j][3] += yv[j][3] * rs * g0.w;
;         xv[j][4] += yv[j][4] * rs * g1.x; xv[j][5] += yv[j][5] * rs * g1.y; xv[j][6] += yv[j][6] * rs * g1.z; xv[j][7] += yv[j][7] * rs * g1.w;
;       }
;     }
;     if (out_f32) {
; #pragma unroll
;       for (int j = 0; j < 2; ++j) {
;         const size_t off = (size_t)row * 1024 + j * 512 + lane * 8;
;         *(float4*)(out_f32 + off) = make_float4(xv[j][0], xv[j][1], xv[j][2], xv[j][3]);
;         *(float4*)(out_f32 + off + 4) = make_float4(xv[j][4], xv[j][5], xv[j][6], xv[j][7]);
;       }
;     }
;     if (write_xb) {
; #pragma unroll
;       for (int j = 0; j < 2; ++j) {
.Lresid_p0_1_wdone:
	v_mul_f32_e32 v80, v32, v32
	v_mul_f32_e32 v81, v33, v33
	v_fmac_f32_e32 v80, v34, v34
	v_fmac_f32_e32 v81, v35, v35
	v_fmac_f32_e32 v80, v36, v36
	v_fmac_f32_e32 v81, v37, v37
	v_fmac_f32_e32 v80, v38, v38
	v_fmac_f32_e32 v81, v39, v39
	v_fmac_f32_e32 v80, v40, v40
	v_fmac_f32_e32 v81, v41, v41
	v_fmac_f32_e32 v80, v42, v42
	v_fmac_f32_e32 v81, v43, v43
	v_fmac_f32_e32 v80, v44, v44
	v_fmac_f32_e32 v81, v45, v45
	v_fmac_f32_e32 v80, v46, v46
	v_fmac_f32_e32 v81, v47, v47
	v_cvt_pk_bf16_f32 v82, v32, v33
	v_cvt_pk_bf16_f32 v83, v34, v35
	v_cvt_pk_bf16_f32 v84, v36, v37
	v_cvt_pk_bf16_f32 v85, v38, v39
	v_cvt_pk_bf16_f32 v86, v40, v41
	v_cvt_pk_bf16_f32 v87, v42, v43
	v_cvt_pk_bf16_f32 v88, v44, v45
	v_cvt_pk_bf16_f32 v89, v46, v47
	v_add_f32_e32 v80, v80, v81
	s_lshl_b32 s1, s0, 11
	v_add_u32_e32 v90, s1, v93
	s_add_u32 s1, s0, s98
	s_add_u32 s1, s1, s98
	s_min_u32 s1, s1, 0xffff
	s_lshl_b32 s1, s1, 12
	v_add_u32_e32 v91, s1, v95
	global_load_dwordx4 v[32:35], v91, s[4:5] offset:-2048
	global_load_dwordx4 v[36:39], v91, s[4:5] offset:-2032
	global_load_dwordx4 v[40:43], v91, s[4:5]
	global_load_dwordx4 v[44:47], v91, s[4:5] offset:16
	global_store_dwordx4 v90, v[82:85], s[6:7]
	global_store_dwordx4 v90, v[86:89], s[6:7] offset:1024
	s_nop 1
	v_add_f32_dpp v80, v80, v80 quad_perm:[1,0,3,2] row_mask:0xf bank_mask:0xf
	s_nop 1
	v_add_f32_dpp v80, v80, v80 quad_perm:[2,3,0,1] row_mask:0xf bank_mask:0xf
	s_nop 1
	v_add_f32_dpp v80, v80, v80 row_half_mirror row_mask:0xf bank_mask:0xf
	s_nop 1
	v_add_f32_dpp v80, v80, v80 row_mirror row_mask:0xf bank_mask:0xf
	s_nop 1
	v_add_f32_dpp v80, v80, v80 row_bcast:15 row_mask:0xa bank_mask:0xf
	s_nop 1
	v_add_f32_dpp v80, v80, v80 row_bcast:31 row_mask:0xc bank_mask:0xf
	s_nop 1
	v_readlane_b32 s1, v80, 63
	s_nop 1
	v_mov_b32_e32 v80, s1
	v_fmamk_f32 v80, v80, 0x3a800000, v229
	v_rsq_f32_e32 v80, v80
	s_lshl_b32 s1, s0, 2
	s_add_u32 s1, s1, 0x1b10e000
	v_mov_b32_e32 v92, s1
	s_mov_b64 exec, 1
	global_store_dword v92, v80, s[86:87]
	s_mov_b64 exec, -1
	s_add_u32 s0, s0, s98
	s_cmp_gt_u32 s0, 0xffff
	s_cbranch_scc1 .Lresid_p0_done
	s_mov_b32 s99, 0
	s_branch .Lresid_p0_loop
.Lresid_p0_done:
	s_waitcnt vmcnt(0)
.LBB0_768:
	s_or_b64 exec, exec, s[2:3]
	s_add_i32 s46, s46, 1
	s_cmp_ge_i32 s46, s47
	s_mov_b64 s[0:1], -1
	s_cbranch_scc0 .LBB0_769
	s_getpc_b64 s[98:99]
